# v10: + dropped 189 dead VGPR copies (pre-loads of row_ror DPP moves) in the up-projection conv epilogue
# speedup vs baseline: 1.0034x; 1.0034x over previous
; __device__ __forceinline__ unsigned cvt_pk_bf16(float lo, float hi) { unsigned r; asm volatile("v_cvt_pk_bf16_f32 %0, %1, %2" : "=v"(r) : "v"(lo), "v"(hi)); return r; }
; template <int CTRL> __device__ __forceinline__ f32x4 dpp4(f32x4 old, f32x4 src) { f32x4 r; r[0] = dppf<CTRL>(old[0], src[0]); r[1] = dppf<CTRL>(old[1], src[1]); r[2] = dppf<CTRL>(old[2], src[2]); r[3] = dppf<CTRL>(old[3], src[3]); return r; }
;     __device__ __forceinline__ void operator()(const f32x4 (&acc)[2][2][4][2], const Unit& u, int wr, int wc, int fr, int fq) const {
;     ...
;                 for (int m = 0; m < 4; ++m) {
;                     const f32x4 va = acc[ai][0][m][n], vb = acc[ai][1][m][n];
;                     f32x4 xa, xb, ya, yb;
;                     if (m == 0) { xa = haf; xb = hbf; } else { xa = dpp4<0x121>(va, acc[ai][0][m - 1][n]); xb = dpp4<0x121>(vb, acc[ai][1][m - 1][n]); }
;                     if (m == 3) { ya = hal; yb = hbl; } else { ya = dpp4<0x12F>(va, acc[ai][0][m + 1][n]); yb = dpp4<0x12F>(vb, acc[ai][1][m + 1][n]); }
;                     const f32x4 pa = dpp4<0x111>(xa, va), pb = dpp4<0x111>(xb, vb);
;                     const f32x4 na = dpp4<0x101>(ya, va), nb = dpp4<0x101>(yb, vb);
;                     const f32x4 ca = ba + w0a * pa + w1a * va + w2a * na, cbv = bb + w0b * pb + w1b * vb + w2b * nb;
;                     if (q == 0 && m == 0) { if (fr == 0) { const size_t o = (size_t)(u.pm * 2 + 0) * 11264 + u.pn * 256 + cl0 + 4 * n;
;                         *(f32x4*)(PART + o) = ca; *(f32x4*)(PART + o + 128) = cbv; *(f32x4*)(RAWB + o) = va; *(f32x4*)(RAWB + o + 128) = vb; } }
;                     if (q == 3 && m == 3) { if (fr == 15) { const size_t o = (size_t)(u.pm * 2 + 1) * 11264 + u.pn * 256 + cl0 + 4 * n;
;                         *(f32x4*)(PART + o) = ca; *(f32x4*)(PART + o + 128) = cbv; *(f32x4*)(RAWB + o) = va; *(f32x4*)(RAWB + o + 128) = vb; } }
;                     const f32x4 h = silu4(ca) * cbv;
;                     u32x2 pk; pk.x = cvt_pk_bf16(h[0], h[1]); pk.y = cvt_pk_bf16(h[2], h[3]);
;                     if (n == 0) pk0[ai][m] = pk;
;                     else { u32x4 w; w.x = pk0[ai][m].x; w.y = pk0[ai][m].y; w.z = pk.x; w.w = pk.y;
;                         __builtin_nontemporal_store(w, (u32x4*)(H + (size_t)(u.pm * BM + ai * HALF + wr * 64 + m * 16 + fr) * 5632 + u.pn * 128 + cl0)); }
.LBB0_939:
	s_lshl_b32 s16, s14, 8
	s_waitcnt lgkmcnt(0)
	v_mov_b32_dpp v174, v158 row_shr:1 row_mask:0xf bank_mask:0xf
	v_mov_b32_dpp v175, v159 row_shr:1 row_mask:0xf bank_mask:0xf
	s_lshl_b32 s15, s94, 1
	s_mul_i32 s0, s94, 0x5800
	s_ashr_i32 s14, s16, 31
	v_mov_b32_dpp v112, v154 row_ror:15 row_mask:0xf bank_mask:0xf
	v_mov_b32_dpp v113, v155 row_ror:15 row_mask:0xf bank_mask:0xf
	s_waitcnt vmcnt(0)
	v_pk_fma_f32 v[174:175], v[138:139], v[174:175], v[146:147]
	s_mul_hi_i32 s1, s15, 0x2c00
	s_add_u32 s0, s0, s16
	v_mov_b32_dpp v172, v110 row_shr:1 row_mask:0xf bank_mask:0xf
	v_mov_b32_dpp v173, v111 row_shr:1 row_mask:0xf bank_mask:0xf
	v_mov_b32_dpp v112, v158 row_shl:1 row_mask:0xf bank_mask:0xf
	v_mov_b32_dpp v113, v159 row_shl:1 row_mask:0xf bank_mask:0xf
	v_pk_fma_f32 v[174:175], v[158:159], v[142:143], v[174:175]
	s_addc_u32 s1, s1, s14
	v_mov_b32_dpp v210, v152 row_ror:15 row_mask:0xf bank_mask:0xf
	v_mov_b32_dpp v211, v153 row_ror:15 row_mask:0xf bank_mask:0xf
	v_mov_b32_dpp v176, v160 row_shr:1 row_mask:0xf bank_mask:0xf
	v_mov_b32_dpp v177, v161 row_shr:1 row_mask:0xf bank_mask:0xf
	v_mov_b32_dpp v170, v108 row_shr:1 row_mask:0xf bank_mask:0xf
	v_mov_b32_dpp v171, v109 row_shr:1 row_mask:0xf bank_mask:0xf
	v_pk_fma_f32 v[174:175], v[130:131], v[112:113], v[174:175]
	v_pk_fma_f32 v[112:113], v[128:129], v[172:173], v[136:137]
	v_mov_b32_e32 v201, s1
	v_or_b32_e32 v200, s0, v188
	v_mov_b32_dpp v198, v156 row_ror:15 row_mask:0xf bank_mask:0xf
	v_mov_b32_dpp v199, v157 row_ror:15 row_mask:0xf bank_mask:0xf
	v_mov_b32_dpp v208, v150 row_ror:15 row_mask:0xf bank_mask:0xf
	v_mov_b32_dpp v209, v151 row_ror:15 row_mask:0xf bank_mask:0xf
	v_mov_b32_dpp v210, v110 row_shl:1 row_mask:0xf bank_mask:0xf
	v_mov_b32_dpp v211, v111 row_shl:1 row_mask:0xf bank_mask:0xf
	v_pk_fma_f32 v[176:177], v[140:141], v[176:177], v[148:149]
	v_pk_fma_f32 v[170:171], v[126:127], v[170:171], v[134:135]
	v_pk_fma_f32 v[112:113], v[110:111], v[124:125], v[112:113]
	v_readlane_b32 s0, v242, 31
	v_mov_b32_dpp v198, v160 row_shl:1 row_mask:0xf bank_mask:0xf
	v_mov_b32_dpp v199, v161 row_shl:1 row_mask:0xf bank_mask:0xf
	v_mov_b32_dpp v208, v108 row_shl:1 row_mask:0xf bank_mask:0xf
	v_mov_b32_dpp v209, v109 row_shl:1 row_mask:0xf bank_mask:0xf
	v_pk_fma_f32 v[176:177], v[160:161], v[144:145], v[176:177]
	v_pk_fma_f32 v[170:171], v[108:109], v[122:123], v[170:171]
	v_pk_fma_f32 v[172:173], v[120:121], v[210:211], v[112:113]
	v_lshlrev_b64 v[112:113], 2, v[200:201]
	v_readlane_b32 s1, v242, 32
	v_pk_fma_f32 v[176:177], v[132:133], v[198:199], v[176:177]
	v_pk_fma_f32 v[170:171], v[118:119], v[208:209], v[170:171]
	v_lshl_add_u64 v[208:209], s[38:39], 0, v[112:113]
	v_lshl_add_u64 v[210:211], s[0:1], 0, v[112:113]
	s_and_saveexec_b64 s[0:1], s[8:9]
	s_cbranch_execz .LBB0_941
	global_store_dwordx4 v[210:211], v[174:177], off
	global_store_dwordx4 v[210:211], v[170:173], off offset:512
	global_store_dwordx4 v[208:209], v[158:161], off
	global_store_dwordx4 v[208:209], v[108:111], off offset:512
.LBB0_941:
	s_or_b64 exec, exec, s[0:1]
	v_mul_f32_e32 v112, 0xbfb8aa3b, v174
	v_mul_f32_e32 v113, 0xbfb8aa3b, v175
	v_exp_f32_e32 v112, v112
	v_exp_f32_e32 v113, v113
	v_mul_f32_e32 v198, 0xbfb8aa3b, v176
	v_exp_f32_e32 v198, v198
	v_mul_f32_e32 v199, 0xbfb8aa3b, v177
	v_exp_f32_e32 v199, v199
	v_add_f32_e32 v112, 1.0, v112
	v_add_f32_e32 v113, 1.0, v113
	v_rcp_f32_e32 v112, v112
	v_rcp_f32_e32 v113, v113
	v_add_f32_e32 v198, 1.0, v198
	v_rcp_f32_e32 v228, v198
	v_add_f32_e32 v198, 1.0, v199
	v_rcp_f32_e32 v229, v198
	v_pk_mul_f32 v[112:113], v[174:175], v[112:113]
	s_or_b32 s0, s15, 1
	v_pk_mul_f32 v[112:113], v[170:171], v[112:113]
	v_pk_mul_f32 v[174:175], v[176:177], v[228:229]
	v_mov_b32_dpp v170, v158 row_ror:1 row_mask:0xf bank_mask:0xf
	v_mov_b32_dpp v171, v159 row_ror:1 row_mask:0xf bank_mask:0xf
	v_pk_mul_f32 v[172:173], v[172:173], v[174:175]
	v_mov_b32_dpp v158, v160 row_ror:1 row_mask:0xf bank_mask:0xf
	v_mov_b32_dpp v159, v161 row_ror:1 row_mask:0xf bank_mask:0xf
	v_cvt_pk_bf16_f32 v112, v112, v113
	v_cvt_pk_bf16_f32 v113, v172, v173
	v_mov_b32_dpp v160, v108 row_ror:1 row_mask:0xf bank_mask:0xf
	v_mov_b32_dpp v161, v109 row_ror:1 row_mask:0xf bank_mask:0xf
	v_mov_b32_dpp v108, v110 row_ror:1 row_mask:0xf bank_mask:0xf
	v_mov_b32_dpp v109, v111 row_ror:1 row_mask:0xf bank_mask:0xf
	v_mov_b32_dpp v170, v154 row_shr:1 row_mask:0xf bank_mask:0xf
	v_mov_b32_dpp v171, v155 row_shr:1 row_mask:0xf bank_mask:0xf
	v_mov_b32_dpp v158, v156 row_shr:1 row_mask:0xf bank_mask:0xf
	v_mov_b32_dpp v159, v157 row_shr:1 row_mask:0xf bank_mask:0xf
	v_mov_b32_dpp v110, v114 row_ror:15 row_mask:0xf bank_mask:0xf
	v_mov_b32_dpp v111, v115 row_ror:15 row_mask:0xf bank_mask:0xf
	v_mov_b32_dpp v172, v116 row_ror:15 row_mask:0xf bank_mask:0xf
	v_mov_b32_dpp v173, v117 row_ror:15 row_mask:0xf bank_mask:0xf
	v_pk_fma_f32 v[158:159], v[140:141], v[158:159], v[148:149]
	v_pk_fma_f32 v[170:171], v[138:139], v[170:171], v[146:147]
	v_mov_b32_dpp v110, v154 row_shl:1 row_mask:0xf bank_mask:0xf
	v_mov_b32_dpp v111, v155 row_shl:1 row_mask:0xf bank_mask:0xf
	v_mov_b32_dpp v172, v156 row_shl:1 row_mask:0xf bank_mask:0xf
	v_mov_b32_dpp v173, v157 row_shl:1 row_mask:0xf bank_mask:0xf
	v_pk_fma_f32 v[170:171], v[154:155], v[142:143], v[170:171]
	v_pk_fma_f32 v[158:159], v[156:157], v[144:145], v[158:159]
	v_pk_fma_f32 v[110:111], v[130:131], v[110:111], v[170:171]
	v_pk_fma_f32 v[158:159], v[132:133], v[172:173], v[158:159]
	v_mul_f32_e32 v170, 0xbfb8aa3b, v110
	v_mul_f32_e32 v171, 0xbfb8aa3b, v111
	v_mul_f32_e32 v172, 0xbfb8aa3b, v158
	v_mul_f32_e32 v173, 0xbfb8aa3b, v159
	v_exp_f32_e32 v170, v170
; __device__ __forceinline__ unsigned cvt_pk_bf16(float lo, float hi) { unsigned r; asm volatile("v_cvt_pk_bf16_f32 %0, %1, %2" : "=v"(r) : "v"(lo), "v"(hi)); return r; }
; template <int CTRL> __device__ __forceinline__ f32x4 dpp4(f32x4 old, f32x4 src) { f32x4 r; r[0] = dppf<CTRL>(old[0], src[0]); r[1] = dppf<CTRL>(old[1], src[1]); r[2] = dppf<CTRL>(old[2], src[2]); r[3] = dppf<CTRL>(old[3], src[3]); return r; }
;     __device__ __forceinline__ void operator()(const f32x4 (&acc)[2][2][4][2], const Unit& u, int wr, int wc, int fr, int fq) const {
;     ...
;                 for (int m = 0; m < 4; ++m) {
;                     const f32x4 va = acc[ai][0][m][n], vb = acc[ai][1][m][n];
;                     f32x4 xa, xb, ya, yb;
;                     if (m == 0) { xa = haf; xb = hbf; } else { xa = dpp4<0x121>(va, acc[ai][0][m - 1][n]); xb = dpp4<0x121>(vb, acc[ai][1][m - 1][n]); }
;                     if (m == 3) { ya = hal; yb = hbl; } else { ya = dpp4<0x12F>(va, acc[ai][0][m + 1][n]); yb = dpp4<0x12F>(vb, acc[ai][1][m + 1][n]); }
;                     const f32x4 pa = dpp4<0x111>(xa, va), pb = dpp4<0x111>(xb, vb);
;                     const f32x4 na = dpp4<0x101>(ya, va), nb = dpp4<0x101>(yb, vb);
;                     const f32x4 ca = ba + w0a * pa + w1a * va + w2a * na, cbv = bb + w0b * pb + w1b * vb + w2b * nb;
;                     if (q == 0 && m == 0) { if (fr == 0) { const size_t o = (size_t)(u.pm * 2 + 0) * 11264 + u.pn * 256 + cl0 + 4 * n;
;                         *(f32x4*)(PART + o) = ca; *(f32x4*)(PART + o + 128) = cbv; *(f32x4*)(RAWB + o) = va; *(f32x4*)(RAWB + o + 128) = vb; } }
;                     if (q == 3 && m == 3) { if (fr == 15) { const size_t o = (size_t)(u.pm * 2 + 1) * 11264 + u.pn * 256 + cl0 + 4 * n;
;                         *(f32x4*)(PART + o) = ca; *(f32x4*)(PART + o + 128) = cbv; *(f32x4*)(RAWB + o) = va; *(f32x4*)(RAWB + o + 128) = vb; } }
;                     const f32x4 h = silu4(ca) * cbv;
;                     u32x2 pk; pk.x = cvt_pk_bf16(h[0], h[1]); pk.y = cvt_pk_bf16(h[2], h[3]);
	v_exp_f32_e32 v171, v171
	v_exp_f32_e32 v172, v172
	v_exp_f32_e32 v173, v173
	v_add_f32_e32 v170, 1.0, v170
	v_add_f32_e32 v171, 1.0, v171
	v_add_f32_e32 v172, 1.0, v172
	v_add_f32_e32 v173, 1.0, v173
	v_rcp_f32_e32 v170, v170
	v_rcp_f32_e32 v171, v171
	v_rcp_f32_e32 v172, v172
	v_rcp_f32_e32 v173, v173
	v_mov_b32_dpp v160, v150 row_shr:1 row_mask:0xf bank_mask:0xf
	v_mov_b32_dpp v161, v151 row_shr:1 row_mask:0xf bank_mask:0xf
	v_mov_b32_dpp v108, v152 row_shr:1 row_mask:0xf bank_mask:0xf
	v_mov_b32_dpp v109, v153 row_shr:1 row_mask:0xf bank_mask:0xf
	v_mov_b32_dpp v174, v104 row_ror:15 row_mask:0xf bank_mask:0xf
	v_mov_b32_dpp v175, v105 row_ror:15 row_mask:0xf bank_mask:0xf
	v_mov_b32_dpp v176, v106 row_ror:15 row_mask:0xf bank_mask:0xf
	v_mov_b32_dpp v177, v107 row_ror:15 row_mask:0xf bank_mask:0xf
	v_pk_fma_f32 v[160:161], v[126:127], v[160:161], v[134:135]
	v_pk_fma_f32 v[108:109], v[128:129], v[108:109], v[136:137]
	v_mov_b32_dpp v174, v150 row_shl:1 row_mask:0xf bank_mask:0xf
	v_mov_b32_dpp v175, v151 row_shl:1 row_mask:0xf bank_mask:0xf
	v_mov_b32_dpp v176, v152 row_shl:1 row_mask:0xf bank_mask:0xf
	v_mov_b32_dpp v177, v153 row_shl:1 row_mask:0xf bank_mask:0xf
	v_pk_fma_f32 v[108:109], v[152:153], v[124:125], v[108:109]
	v_pk_fma_f32 v[160:161], v[150:151], v[122:123], v[160:161]
	v_pk_fma_f32 v[108:109], v[120:121], v[176:177], v[108:109]
	v_pk_fma_f32 v[160:161], v[118:119], v[174:175], v[160:161]
	v_pk_mul_f32 v[110:111], v[110:111], v[170:171]
	v_pk_mul_f32 v[158:159], v[158:159], v[172:173]
	v_pk_mul_f32 v[110:111], v[160:161], v[110:111]
	v_pk_mul_f32 v[108:109], v[108:109], v[158:159]
	v_cvt_pk_bf16_f32 v110, v110, v111
	v_cvt_pk_bf16_f32 v111, v108, v109
	v_mov_b32_dpp v108, v154 row_ror:1 row_mask:0xf bank_mask:0xf
	v_mov_b32_dpp v109, v155 row_ror:1 row_mask:0xf bank_mask:0xf
	s_nop 0
	v_mov_b32_dpp v108, v114 row_shr:1 row_mask:0xf bank_mask:0xf
	v_mov_b32_dpp v154, v156 row_ror:1 row_mask:0xf bank_mask:0xf
	v_mov_b32_dpp v155, v157 row_ror:1 row_mask:0xf bank_mask:0xf
	v_mov_b32_dpp v109, v115 row_shr:1 row_mask:0xf bank_mask:0xf
	v_mov_b32_dpp v156, v150 row_ror:1 row_mask:0xf bank_mask:0xf
	v_mov_b32_dpp v157, v151 row_ror:1 row_mask:0xf bank_mask:0xf
	v_mov_b32_dpp v154, v116 row_shr:1 row_mask:0xf bank_mask:0xf
	v_mov_b32_dpp v150, v152 row_ror:1 row_mask:0xf bank_mask:0xf
	v_mov_b32_dpp v151, v153 row_ror:1 row_mask:0xf bank_mask:0xf
	v_mov_b32_dpp v155, v117 row_shr:1 row_mask:0xf bank_mask:0xf
	v_mov_b32_dpp v152, v100 row_ror:15 row_mask:0xf bank_mask:0xf
	v_mov_b32_dpp v153, v101 row_ror:15 row_mask:0xf bank_mask:0xf
	v_mov_b32_dpp v158, v102 row_ror:15 row_mask:0xf bank_mask:0xf
	v_mov_b32_dpp v159, v103 row_ror:15 row_mask:0xf bank_mask:0xf
	v_pk_fma_f32 v[154:155], v[140:141], v[154:155], v[148:149]
	v_pk_fma_f32 v[108:109], v[138:139], v[108:109], v[146:147]
	v_mov_b32_dpp v152, v114 row_shl:1 row_mask:0xf bank_mask:0xf
	v_mov_b32_dpp v153, v115 row_shl:1 row_mask:0xf bank_mask:0xf
	v_mov_b32_dpp v158, v116 row_shl:1 row_mask:0xf bank_mask:0xf
	v_mov_b32_dpp v159, v117 row_shl:1 row_mask:0xf bank_mask:0xf
	v_pk_fma_f32 v[108:109], v[114:115], v[142:143], v[108:109]
	v_pk_fma_f32 v[154:155], v[116:117], v[144:145], v[154:155]
	v_mov_b32_dpp v156, v104 row_shr:1 row_mask:0xf bank_mask:0xf
	v_mov_b32_dpp v157, v105 row_shr:1 row_mask:0xf bank_mask:0xf
	v_pk_fma_f32 v[154:155], v[132:133], v[158:159], v[154:155]
	v_pk_fma_f32 v[108:109], v[130:131], v[152:153], v[108:109]
	v_pk_fma_f32 v[152:153], v[126:127], v[156:157], v[134:135]
	v_mul_f32_e32 v156, 0xbfb8aa3b, v108
	v_mul_f32_e32 v157, 0xbfb8aa3b, v109
	v_mul_f32_e32 v158, 0xbfb8aa3b, v154
	v_mul_f32_e32 v159, 0xbfb8aa3b, v155
	v_exp_f32_e32 v156, v156
	v_exp_f32_e32 v157, v157
	v_exp_f32_e32 v158, v158
	v_exp_f32_e32 v159, v159
	v_add_f32_e32 v156, 1.0, v156
	v_add_f32_e32 v157, 1.0, v157
	v_add_f32_e32 v158, 1.0, v158
	v_add_f32_e32 v159, 1.0, v159
	v_rcp_f32_e32 v156, v156
	v_rcp_f32_e32 v157, v157
	v_rcp_f32_e32 v158, v158
	v_rcp_f32_e32 v159, v159
	v_mov_b32_dpp v150, v106 row_shr:1 row_mask:0xf bank_mask:0xf
; template <int CTRL> __device__ __forceinline__ f32x4 dpp4(f32x4 old, f32x4 src) { f32x4 r; r[0] = dppf<CTRL>(old[0], src[0]); r[1] = dppf<CTRL>(old[1], src[1]); r[2] = dppf<CTRL>(old[2], src[2]); r[3] = dppf<CTRL>(old[3], src[3]); return r; }
;     __device__ __forceinline__ void operator()(const f32x4 (&acc)[2][2][4][2], const Unit& u, int wr, int wc, int fr, int fq) const {
;     ...
;                 for (int m = 0; m < 4; ++m) {
;                     const f32x4 va = acc[ai][0][m][n], vb = acc[ai][1][m][n];
;                     f32x4 xa, xb, ya, yb;
;                     if (m == 0) { xa = haf; xb = hbf; } else { xa = dpp4<0x121>(va, acc[ai][0][m - 1][n]); xb = dpp4<0x121>(vb, acc[ai][1][m - 1][n]); }
;                     if (m == 3) { ya = hal; yb = hbl; } else { ya = dpp4<0x12F>(va, acc[ai][0][m + 1][n]); yb = dpp4<0x12F>(vb, acc[ai][1][m + 1][n]); }
;                     const f32x4 pa = dpp4<0x111>(xa, va), pb = dpp4<0x111>(xb, vb);
;                     const f32x4 na = dpp4<0x101>(ya, va), nb = dpp4<0x101>(yb, vb);
;                     const f32x4 ca = ba + w0a * pa + w1a * va + w2a * na, cbv = bb + w0b * pb + w1b * vb + w2b * nb;
;                     if (q == 0 && m == 0) { if (fr == 0) { const size_t o = (size_t)(u.pm * 2 + 0) * 11264 + u.pn * 256 + cl0 + 4 * n;
;                         *(f32x4*)(PART + o) = ca; *(f32x4*)(PART + o + 128) = cbv; *(f32x4*)(RAWB + o) = va; *(f32x4*)(RAWB + o + 128) = vb; } }
;                     if (q == 3 && m == 3) { if (fr == 15) { const size_t o = (size_t)(u.pm * 2 + 1) * 11264 + u.pn * 256 + cl0 + 4 * n;
;                         *(f32x4*)(PART + o) = ca; *(f32x4*)(PART + o + 128) = cbv; *(f32x4*)(RAWB + o) = va; *(f32x4*)(RAWB + o + 128) = vb; } }
	v_mov_b32_dpp v151, v107 row_shr:1 row_mask:0xf bank_mask:0xf
	v_mov_b32_dpp v160, v96 row_ror:15 row_mask:0xf bank_mask:0xf
	v_mov_b32_dpp v161, v97 row_ror:15 row_mask:0xf bank_mask:0xf
	v_mov_b32_dpp v170, v98 row_ror:15 row_mask:0xf bank_mask:0xf
	v_mov_b32_dpp v171, v99 row_ror:15 row_mask:0xf bank_mask:0xf
	v_pk_fma_f32 v[150:151], v[128:129], v[150:151], v[136:137]
	v_mov_b32_dpp v160, v104 row_shl:1 row_mask:0xf bank_mask:0xf
	v_mov_b32_dpp v161, v105 row_shl:1 row_mask:0xf bank_mask:0xf
	v_mov_b32_dpp v170, v106 row_shl:1 row_mask:0xf bank_mask:0xf
	v_mov_b32_dpp v171, v107 row_shl:1 row_mask:0xf bank_mask:0xf
	v_pk_fma_f32 v[150:151], v[106:107], v[124:125], v[150:151]
	v_pk_fma_f32 v[152:153], v[104:105], v[122:123], v[152:153]
	v_pk_fma_f32 v[150:151], v[120:121], v[170:171], v[150:151]
	v_pk_fma_f32 v[152:153], v[118:119], v[160:161], v[152:153]
	v_pk_mul_f32 v[108:109], v[108:109], v[156:157]
	v_pk_mul_f32 v[154:155], v[154:155], v[158:159]
	v_pk_mul_f32 v[108:109], v[152:153], v[108:109]
	v_pk_mul_f32 v[150:151], v[150:151], v[154:155]
	v_cvt_pk_bf16_f32 v108, v108, v109
	v_cvt_pk_bf16_f32 v109, v150, v151
	v_mov_b32_dpp v150, v114 row_ror:1 row_mask:0xf bank_mask:0xf
	v_mov_b32_dpp v151, v115 row_ror:1 row_mask:0xf bank_mask:0xf
	s_nop 0
	v_mov_b32_dpp v150, v100 row_shr:1 row_mask:0xf bank_mask:0xf
	v_mov_b32_dpp v114, v116 row_ror:1 row_mask:0xf bank_mask:0xf
	v_mov_b32_dpp v115, v117 row_ror:1 row_mask:0xf bank_mask:0xf
	v_mov_b32_dpp v151, v101 row_shr:1 row_mask:0xf bank_mask:0xf
	v_mov_b32_dpp v114, v102 row_shr:1 row_mask:0xf bank_mask:0xf
	v_mov_b32_dpp v115, v103 row_shr:1 row_mask:0xf bank_mask:0xf
	s_mul_hi_i32 s1, s0, 0x2c00
	s_mulk_i32 s0, 0x2c00
	v_mov_b32_dpp v116, v104 row_ror:1 row_mask:0xf bank_mask:0xf
	v_mov_b32_dpp v117, v105 row_ror:1 row_mask:0xf bank_mask:0xf
	v_mov_b32_dpp v152, v106 row_ror:1 row_mask:0xf bank_mask:0xf
	v_mov_b32_dpp v153, v107 row_ror:1 row_mask:0xf bank_mask:0xf
	v_pk_fma_f32 v[104:105], v[140:141], v[114:115], v[148:149]
	v_pk_fma_f32 v[106:107], v[138:139], v[150:151], v[146:147]
	s_add_u32 s0, s0, s16
	v_mov_b32_dpp v116, v96 row_shr:1 row_mask:0xf bank_mask:0xf
	v_mov_b32_dpp v117, v97 row_shr:1 row_mask:0xf bank_mask:0xf
	v_mov_b32_dpp v152, v98 row_shr:1 row_mask:0xf bank_mask:0xf
	v_mov_b32_dpp v153, v99 row_shr:1 row_mask:0xf bank_mask:0xf
	v_mov_b32_dpp v162, v100 row_shl:1 row_mask:0xf bank_mask:0xf
	v_mov_b32_dpp v163, v101 row_shl:1 row_mask:0xf bank_mask:0xf
	v_mov_b32_dpp v164, v102 row_shl:1 row_mask:0xf bank_mask:0xf
	v_mov_b32_dpp v165, v103 row_shl:1 row_mask:0xf bank_mask:0xf
	v_pk_fma_f32 v[114:115], v[100:101], v[142:143], v[106:107]
	v_pk_fma_f32 v[104:105], v[102:103], v[144:145], v[104:105]
	s_addc_u32 s1, s1, s14
	v_pk_fma_f32 v[106:107], v[132:133], v[164:165], v[104:105]
	v_pk_fma_f32 v[104:105], v[130:131], v[162:163], v[114:115]
	v_pk_fma_f32 v[114:115], v[128:129], v[152:153], v[136:137]
	v_pk_fma_f32 v[116:117], v[126:127], v[116:117], v[134:135]
	v_mov_b32_e32 v199, s1
	v_or_b32_e32 v198, s0, v188
	v_mov_b32_dpp v166, v96 row_shl:1 row_mask:0xf bank_mask:0xf
	v_mov_b32_dpp v167, v97 row_shl:1 row_mask:0xf bank_mask:0xf
	v_mov_b32_dpp v168, v98 row_shl:1 row_mask:0xf bank_mask:0xf
	v_mov_b32_dpp v169, v99 row_shl:1 row_mask:0xf bank_mask:0xf
	v_pk_fma_f32 v[150:151], v[96:97], v[122:123], v[116:117]
	v_pk_fma_f32 v[114:115], v[98:99], v[124:125], v[114:115]
	v_readlane_b32 s0, v242, 31
	v_pk_fma_f32 v[116:117], v[120:121], v[168:169], v[114:115]
	v_pk_fma_f32 v[114:115], v[118:119], v[166:167], v[150:151]
	v_lshlrev_b64 v[150:151], 2, v[198:199]
	v_readlane_b32 s1, v242, 32
	v_lshl_add_u64 v[154:155], s[38:39], 0, v[150:151]
	s_nop 0
	v_lshl_add_u64 v[156:157], s[0:1], 0, v[150:151]
	s_and_saveexec_b64 s[0:1], s[50:51]
	s_cbranch_execz .LBB0_943
	global_store_dwordx4 v[156:157], v[104:107], off
	global_store_dwordx4 v[156:157], v[114:117], off offset:512
	global_store_dwordx4 v[154:155], v[100:103], off
	global_store_dwordx4 v[154:155], v[96:99], off offset:512

; __device__ __forceinline__ unsigned cvt_pk_bf16(float lo, float hi) { unsigned r; asm volatile("v_cvt_pk_bf16_f32 %0, %1, %2" : "=v"(r) : "v"(lo), "v"(hi)); return r; }
; template <int CTRL> __device__ __forceinline__ f32x4 dpp4(f32x4 old, f32x4 src) { f32x4 r; r[0] = dppf<CTRL>(old[0], src[0]); r[1] = dppf<CTRL>(old[1], src[1]); r[2] = dppf<CTRL>(old[2], src[2]); r[3] = dppf<CTRL>(old[3], src[3]); return r; }
;     __device__ __forceinline__ void operator()(const f32x4 (&acc)[2][2][4][2], const Unit& u, int wr, int wc, int fr, int fq) const {
;     ...
;                 for (int m = 0; m < 4; ++m) {
;                     const f32x4 va = acc[ai][0][m][n], vb = acc[ai][1][m][n];
;                     f32x4 xa, xb, ya, yb;
;                     if (m == 0) { xa = haf; xb = hbf; } else { xa = dpp4<0x121>(va, acc[ai][0][m - 1][n]); xb = dpp4<0x121>(vb, acc[ai][1][m - 1][n]); }
;                     if (m == 3) { ya = hal; yb = hbl; } else { ya = dpp4<0x12F>(va, acc[ai][0][m + 1][n]); yb = dpp4<0x12F>(vb, acc[ai][1][m + 1][n]); }
;                     const f32x4 pa = dpp4<0x111>(xa, va), pb = dpp4<0x111>(xb, vb);
;                     const f32x4 na = dpp4<0x101>(ya, va), nb = dpp4<0x101>(yb, vb);
;                     const f32x4 ca = ba + w0a * pa + w1a * va + w2a * na, cbv = bb + w0b * pb + w1b * vb + w2b * nb;
;                     if (q == 0 && m == 0) { if (fr == 0) { const size_t o = (size_t)(u.pm * 2 + 0) * 11264 + u.pn * 256 + cl0 + 4 * n;
;                         *(f32x4*)(PART + o) = ca; *(f32x4*)(PART + o + 128) = cbv; *(f32x4*)(RAWB + o) = va; *(f32x4*)(RAWB + o + 128) = vb; } }
;                     if (q == 3 && m == 3) { if (fr == 15) { const size_t o = (size_t)(u.pm * 2 + 1) * 11264 + u.pn * 256 + cl0 + 4 * n;
;                         *(f32x4*)(PART + o) = ca; *(f32x4*)(PART + o + 128) = cbv; *(f32x4*)(RAWB + o) = va; *(f32x4*)(RAWB + o + 128) = vb; } }
;                     const f32x4 h = silu4(ca) * cbv;
;                     u32x2 pk; pk.x = cvt_pk_bf16(h[0], h[1]); pk.y = cvt_pk_bf16(h[2], h[3]);
.LBB0_947:
	s_waitcnt lgkmcnt(1)
	v_mov_b32_dpp v150, v92 row_shr:1 row_mask:0xf bank_mask:0xf
	v_mov_b32_dpp v151, v93 row_shr:1 row_mask:0xf bank_mask:0xf
	v_mov_b32_dpp v96, v84 row_ror:15 row_mask:0xf bank_mask:0xf
	v_mov_b32_dpp v97, v85 row_ror:15 row_mask:0xf bank_mask:0xf
	v_pk_fma_f32 v[150:151], v[138:139], v[150:151], v[146:147]
	v_mov_b32_dpp v152, v94 row_shr:1 row_mask:0xf bank_mask:0xf
	v_mov_b32_dpp v153, v95 row_shr:1 row_mask:0xf bank_mask:0xf
	s_waitcnt lgkmcnt(0)
	v_mov_b32_dpp v114, v88 row_shr:1 row_mask:0xf bank_mask:0xf
	v_mov_b32_dpp v115, v89 row_shr:1 row_mask:0xf bank_mask:0xf
	v_mov_b32_dpp v116, v90 row_shr:1 row_mask:0xf bank_mask:0xf
	v_mov_b32_dpp v117, v91 row_shr:1 row_mask:0xf bank_mask:0xf
	v_mov_b32_dpp v96, v92 row_shl:1 row_mask:0xf bank_mask:0xf
	v_mov_b32_dpp v97, v93 row_shl:1 row_mask:0xf bank_mask:0xf
	v_pk_fma_f32 v[150:151], v[92:93], v[142:143], v[150:151]
	v_mov_b32_dpp v158, v86 row_ror:15 row_mask:0xf bank_mask:0xf
	v_mov_b32_dpp v159, v87 row_ror:15 row_mask:0xf bank_mask:0xf
	v_mov_b32_dpp v160, v80 row_ror:15 row_mask:0xf bank_mask:0xf
	v_mov_b32_dpp v161, v81 row_ror:15 row_mask:0xf bank_mask:0xf
	v_mov_b32_dpp v162, v82 row_ror:15 row_mask:0xf bank_mask:0xf
	v_mov_b32_dpp v163, v83 row_ror:15 row_mask:0xf bank_mask:0xf
	v_pk_fma_f32 v[152:153], v[140:141], v[152:153], v[148:149]
	v_pk_fma_f32 v[150:151], v[130:131], v[96:97], v[150:151]
	v_pk_fma_f32 v[96:97], v[128:129], v[116:117], v[136:137]
	v_pk_fma_f32 v[114:115], v[126:127], v[114:115], v[134:135]
	v_mov_b32_dpp v158, v94 row_shl:1 row_mask:0xf bank_mask:0xf
	v_mov_b32_dpp v159, v95 row_shl:1 row_mask:0xf bank_mask:0xf
	v_mov_b32_dpp v160, v88 row_shl:1 row_mask:0xf bank_mask:0xf
	v_mov_b32_dpp v161, v89 row_shl:1 row_mask:0xf bank_mask:0xf
	v_mov_b32_dpp v162, v90 row_shl:1 row_mask:0xf bank_mask:0xf
	v_mov_b32_dpp v163, v91 row_shl:1 row_mask:0xf bank_mask:0xf
	v_pk_fma_f32 v[152:153], v[94:95], v[144:145], v[152:153]
	v_pk_fma_f32 v[114:115], v[88:89], v[122:123], v[114:115]
	v_pk_fma_f32 v[96:97], v[90:91], v[124:125], v[96:97]
	v_pk_fma_f32 v[152:153], v[132:133], v[158:159], v[152:153]
	v_pk_fma_f32 v[116:117], v[120:121], v[162:163], v[96:97]
	v_pk_fma_f32 v[114:115], v[118:119], v[160:161], v[114:115]
	s_and_saveexec_b64 s[0:1], s[10:11]
	s_cbranch_execz .LBB0_949
	global_store_dwordx4 v[210:211], v[150:153], off
	global_store_dwordx4 v[210:211], v[114:117], off offset:512
	global_store_dwordx4 v[208:209], v[92:95], off
	global_store_dwordx4 v[208:209], v[88:91], off offset:512
.LBB0_949:
	s_or_b64 exec, exec, s[0:1]
	v_mul_f32_e32 v96, 0xbfb8aa3b, v150
	v_mul_f32_e32 v97, 0xbfb8aa3b, v151
	v_exp_f32_e32 v96, v96
	v_exp_f32_e32 v97, v97
	v_mul_f32_e32 v158, 0xbfb8aa3b, v152
	v_mul_f32_e32 v159, 0xbfb8aa3b, v153
	v_exp_f32_e32 v158, v158
	v_exp_f32_e32 v159, v159
	v_add_f32_e32 v96, 1.0, v96
	v_add_f32_e32 v97, 1.0, v97
	v_rcp_f32_e32 v96, v96
	v_rcp_f32_e32 v97, v97
	v_add_f32_e32 v158, 1.0, v158
	v_add_f32_e32 v159, 1.0, v159
	v_rcp_f32_e32 v158, v158
	v_rcp_f32_e32 v159, v159
	v_pk_mul_f32 v[96:97], v[150:151], v[96:97]
	v_mov_b32_dpp v100, v68 row_shl:1 row_mask:0xf bank_mask:0xf
	v_pk_mul_f32 v[96:97], v[114:115], v[96:97]
	v_pk_mul_f32 v[150:151], v[152:153], v[158:159]
	v_mov_b32_dpp v114, v92 row_ror:1 row_mask:0xf bank_mask:0xf
	v_mov_b32_dpp v115, v93 row_ror:1 row_mask:0xf bank_mask:0xf
	v_pk_mul_f32 v[116:117], v[116:117], v[150:151]
	v_mov_b32_dpp v92, v94 row_ror:1 row_mask:0xf bank_mask:0xf
	v_mov_b32_dpp v93, v95 row_ror:1 row_mask:0xf bank_mask:0xf
	v_cvt_pk_bf16_f32 v96, v96, v97
	v_cvt_pk_bf16_f32 v97, v116, v117
	v_mov_b32_dpp v94, v88 row_ror:1 row_mask:0xf bank_mask:0xf
	v_mov_b32_dpp v95, v89 row_ror:1 row_mask:0xf bank_mask:0xf
	v_mov_b32_dpp v88, v90 row_ror:1 row_mask:0xf bank_mask:0xf
	v_mov_b32_dpp v89, v91 row_ror:1 row_mask:0xf bank_mask:0xf
	v_mov_b32_dpp v114, v84 row_shr:1 row_mask:0xf bank_mask:0xf
	v_mov_b32_dpp v115, v85 row_shr:1 row_mask:0xf bank_mask:0xf
	v_mov_b32_dpp v92, v86 row_shr:1 row_mask:0xf bank_mask:0xf
	v_mov_b32_dpp v93, v87 row_shr:1 row_mask:0xf bank_mask:0xf
	v_mov_b32_dpp v90, v76 row_ror:15 row_mask:0xf bank_mask:0xf
	v_mov_b32_dpp v91, v77 row_ror:15 row_mask:0xf bank_mask:0xf
	v_mov_b32_dpp v116, v78 row_ror:15 row_mask:0xf bank_mask:0xf
	v_mov_b32_dpp v117, v79 row_ror:15 row_mask:0xf bank_mask:0xf
	v_pk_fma_f32 v[92:93], v[140:141], v[92:93], v[148:149]
	v_pk_fma_f32 v[114:115], v[138:139], v[114:115], v[146:147]
	v_mov_b32_dpp v90, v84 row_shl:1 row_mask:0xf bank_mask:0xf
	v_mov_b32_dpp v91, v85 row_shl:1 row_mask:0xf bank_mask:0xf
	v_mov_b32_dpp v116, v86 row_shl:1 row_mask:0xf bank_mask:0xf
	v_mov_b32_dpp v117, v87 row_shl:1 row_mask:0xf bank_mask:0xf
	v_pk_fma_f32 v[114:115], v[84:85], v[142:143], v[114:115]
	v_pk_fma_f32 v[92:93], v[86:87], v[144:145], v[92:93]
	v_pk_fma_f32 v[90:91], v[130:131], v[90:91], v[114:115]
	v_pk_fma_f32 v[92:93], v[132:133], v[116:117], v[92:93]
	v_mul_f32_e32 v114, 0xbfb8aa3b, v90
	v_mul_f32_e32 v115, 0xbfb8aa3b, v91
	v_mul_f32_e32 v116, 0xbfb8aa3b, v92
	v_mul_f32_e32 v117, 0xbfb8aa3b, v93
	v_exp_f32_e32 v114, v114
	v_exp_f32_e32 v115, v115
	v_exp_f32_e32 v116, v116
	v_exp_f32_e32 v117, v117
	v_add_f32_e32 v114, 1.0, v114
	v_add_f32_e32 v115, 1.0, v115
	v_add_f32_e32 v116, 1.0, v116
	v_add_f32_e32 v117, 1.0, v117
	v_rcp_f32_e32 v114, v114
	v_rcp_f32_e32 v115, v115
	v_rcp_f32_e32 v116, v116
	v_rcp_f32_e32 v117, v117
	v_mov_b32_dpp v94, v80 row_shr:1 row_mask:0xf bank_mask:0xf
	v_mov_b32_dpp v95, v81 row_shr:1 row_mask:0xf bank_mask:0xf
	v_mov_b32_dpp v88, v82 row_shr:1 row_mask:0xf bank_mask:0xf
; template <int CTRL> __device__ __forceinline__ f32x4 dpp4(f32x4 old, f32x4 src) { f32x4 r; r[0] = dppf<CTRL>(old[0], src[0]); r[1] = dppf<CTRL>(old[1], src[1]); r[2] = dppf<CTRL>(old[2], src[2]); r[3] = dppf<CTRL>(old[3], src[3]); return r; }
;     __device__ __forceinline__ void operator()(const f32x4 (&acc)[2][2][4][2], const Unit& u, int wr, int wc, int fr, int fq) const {
;     ...
;                 for (int m = 0; m < 4; ++m) {
;                     const f32x4 va = acc[ai][0][m][n], vb = acc[ai][1][m][n];
;                     f32x4 xa, xb, ya, yb;
;                     if (m == 0) { xa = haf; xb = hbf; } else { xa = dpp4<0x121>(va, acc[ai][0][m - 1][n]); xb = dpp4<0x121>(vb, acc[ai][1][m - 1][n]); }
;                     if (m == 3) { ya = hal; yb = hbl; } else { ya = dpp4<0x12F>(va, acc[ai][0][m + 1][n]); yb = dpp4<0x12F>(vb, acc[ai][1][m + 1][n]); }
;                     const f32x4 pa = dpp4<0x111>(xa, va), pb = dpp4<0x111>(xb, vb);
;                     const f32x4 na = dpp4<0x101>(ya, va), nb = dpp4<0x101>(yb, vb);
;                     const f32x4 ca = ba + w0a * pa + w1a * va + w2a * na, cbv = bb + w0b * pb + w1b * vb + w2b * nb;
;                     if (q == 0 && m == 0) { if (fr == 0) { const size_t o = (size_t)(u.pm * 2 + 0) * 11264 + u.pn * 256 + cl0 + 4 * n;
;                         *(f32x4*)(PART + o) = ca; *(f32x4*)(PART + o + 128) = cbv; *(f32x4*)(RAWB + o) = va; *(f32x4*)(RAWB + o + 128) = vb; } }
;                     if (q == 3 && m == 3) { if (fr == 15) { const size_t o = (size_t)(u.pm * 2 + 1) * 11264 + u.pn * 256 + cl0 + 4 * n;
;                         *(f32x4*)(PART + o) = ca; *(f32x4*)(PART + o + 128) = cbv; *(f32x4*)(RAWB + o) = va; *(f32x4*)(RAWB + o + 128) = vb; } }
	v_mov_b32_dpp v89, v83 row_shr:1 row_mask:0xf bank_mask:0xf
	v_mov_b32_dpp v150, v72 row_ror:15 row_mask:0xf bank_mask:0xf
	v_mov_b32_dpp v151, v73 row_ror:15 row_mask:0xf bank_mask:0xf
	v_mov_b32_dpp v152, v74 row_ror:15 row_mask:0xf bank_mask:0xf
	v_mov_b32_dpp v153, v75 row_ror:15 row_mask:0xf bank_mask:0xf
	v_pk_fma_f32 v[94:95], v[126:127], v[94:95], v[134:135]
	v_pk_fma_f32 v[88:89], v[128:129], v[88:89], v[136:137]
	v_mov_b32_dpp v150, v80 row_shl:1 row_mask:0xf bank_mask:0xf
	v_mov_b32_dpp v151, v81 row_shl:1 row_mask:0xf bank_mask:0xf
	v_mov_b32_dpp v152, v82 row_shl:1 row_mask:0xf bank_mask:0xf
	v_mov_b32_dpp v153, v83 row_shl:1 row_mask:0xf bank_mask:0xf
	v_pk_fma_f32 v[88:89], v[82:83], v[124:125], v[88:89]
	v_pk_fma_f32 v[94:95], v[80:81], v[122:123], v[94:95]
	v_pk_fma_f32 v[88:89], v[120:121], v[152:153], v[88:89]
	v_pk_fma_f32 v[94:95], v[118:119], v[150:151], v[94:95]
	v_pk_mul_f32 v[90:91], v[90:91], v[114:115]
	v_pk_mul_f32 v[92:93], v[92:93], v[116:117]
	v_mov_b32_e32 v114, v74
	v_pk_mul_f32 v[92:93], v[88:89], v[92:93]
	v_pk_mul_f32 v[88:89], v[94:95], v[90:91]
	v_cvt_pk_bf16_f32 v88, v88, v89
	v_cvt_pk_bf16_f32 v89, v92, v93
	v_mov_b32_dpp v90, v84 row_ror:1 row_mask:0xf bank_mask:0xf
	v_mov_b32_dpp v91, v85 row_ror:1 row_mask:0xf bank_mask:0xf
	v_mov_b32_dpp v84, v86 row_ror:1 row_mask:0xf bank_mask:0xf
	v_mov_b32_dpp v85, v87 row_ror:1 row_mask:0xf bank_mask:0xf
	v_mov_b32_dpp v90, v76 row_shr:1 row_mask:0xf bank_mask:0xf
	v_mov_b32_dpp v86, v80 row_ror:1 row_mask:0xf bank_mask:0xf
	v_mov_b32_dpp v87, v81 row_ror:1 row_mask:0xf bank_mask:0xf
	v_mov_b32_dpp v91, v77 row_shr:1 row_mask:0xf bank_mask:0xf
	v_mov_b32_dpp v80, v82 row_ror:1 row_mask:0xf bank_mask:0xf
	v_mov_b32_dpp v81, v83 row_ror:1 row_mask:0xf bank_mask:0xf
	v_mov_b32_dpp v84, v78 row_shr:1 row_mask:0xf bank_mask:0xf
	v_mov_b32_dpp v85, v79 row_shr:1 row_mask:0xf bank_mask:0xf
	v_mov_b32_dpp v82, v68 row_ror:15 row_mask:0xf bank_mask:0xf
	v_mov_b32_dpp v83, v69 row_ror:15 row_mask:0xf bank_mask:0xf
	v_mov_b32_dpp v92, v70 row_ror:15 row_mask:0xf bank_mask:0xf
	v_mov_b32_dpp v93, v71 row_ror:15 row_mask:0xf bank_mask:0xf
	v_pk_fma_f32 v[84:85], v[140:141], v[84:85], v[148:149]
	v_pk_fma_f32 v[90:91], v[138:139], v[90:91], v[146:147]
	v_mov_b32_dpp v82, v76 row_shl:1 row_mask:0xf bank_mask:0xf
	v_mov_b32_dpp v83, v77 row_shl:1 row_mask:0xf bank_mask:0xf
	v_mov_b32_dpp v92, v78 row_shl:1 row_mask:0xf bank_mask:0xf
	v_mov_b32_dpp v93, v79 row_shl:1 row_mask:0xf bank_mask:0xf
	v_pk_fma_f32 v[90:91], v[76:77], v[142:143], v[90:91]
	v_pk_fma_f32 v[84:85], v[78:79], v[144:145], v[84:85]
	v_pk_fma_f32 v[82:83], v[130:131], v[82:83], v[90:91]
	v_pk_fma_f32 v[84:85], v[132:133], v[92:93], v[84:85]
	v_mul_f32_e32 v90, 0xbfb8aa3b, v82
	v_mul_f32_e32 v91, 0xbfb8aa3b, v83
	v_mul_f32_e32 v92, 0xbfb8aa3b, v84
	v_mul_f32_e32 v93, 0xbfb8aa3b, v85
	v_exp_f32_e32 v90, v90
	v_exp_f32_e32 v91, v91
	v_exp_f32_e32 v92, v92
	v_exp_f32_e32 v93, v93
	v_add_f32_e32 v90, 1.0, v90
	v_add_f32_e32 v91, 1.0, v91
	v_add_f32_e32 v92, 1.0, v92
	v_add_f32_e32 v93, 1.0, v93
	v_rcp_f32_e32 v90, v90
	v_rcp_f32_e32 v91, v91
	v_rcp_f32_e32 v92, v92
	v_rcp_f32_e32 v93, v93
	v_mov_b32_dpp v86, v72 row_shr:1 row_mask:0xf bank_mask:0xf
	v_mov_b32_dpp v87, v73 row_shr:1 row_mask:0xf bank_mask:0xf
	v_mov_b32_dpp v80, v74 row_shr:1 row_mask:0xf bank_mask:0xf
	v_mov_b32_dpp v81, v75 row_shr:1 row_mask:0xf bank_mask:0xf
	v_mov_b32_dpp v94, v64 row_ror:15 row_mask:0xf bank_mask:0xf
	v_mov_b32_dpp v95, v65 row_ror:15 row_mask:0xf bank_mask:0xf
	v_mov_b32_dpp v114, v66 row_ror:15 row_mask:0xf bank_mask:0xf
	v_mov_b32_dpp v115, v67 row_ror:15 row_mask:0xf bank_mask:0xf
	v_pk_fma_f32 v[86:87], v[126:127], v[86:87], v[134:135]
	v_pk_fma_f32 v[80:81], v[128:129], v[80:81], v[136:137]
	v_mov_b32_dpp v94, v72 row_shl:1 row_mask:0xf bank_mask:0xf
	v_mov_b32_dpp v95, v73 row_shl:1 row_mask:0xf bank_mask:0xf
	v_mov_b32_dpp v114, v74 row_shl:1 row_mask:0xf bank_mask:0xf
	v_mov_b32_dpp v115, v75 row_shl:1 row_mask:0xf bank_mask:0xf
	v_pk_fma_f32 v[80:81], v[74:75], v[124:125], v[80:81]
	v_pk_fma_f32 v[86:87], v[72:73], v[122:123], v[86:87]
	v_pk_fma_f32 v[80:81], v[120:121], v[114:115], v[80:81]
	v_pk_fma_f32 v[86:87], v[118:119], v[94:95], v[86:87]
	v_pk_mul_f32 v[82:83], v[82:83], v[90:91]
	v_pk_mul_f32 v[84:85], v[84:85], v[92:93]
	v_mov_b32_dpp v101, v69 row_shl:1 row_mask:0xf bank_mask:0xf
	v_pk_mul_f32 v[84:85], v[80:81], v[84:85]
	v_pk_mul_f32 v[80:81], v[86:87], v[82:83]
	v_cvt_pk_bf16_f32 v80, v80, v81
	v_cvt_pk_bf16_f32 v81, v84, v85
	v_mov_b32_dpp v82, v76 row_ror:1 row_mask:0xf bank_mask:0xf
	v_mov_b32_dpp v83, v77 row_ror:1 row_mask:0xf bank_mask:0xf
	v_mov_b32_dpp v76, v78 row_ror:1 row_mask:0xf bank_mask:0xf
	v_mov_b32_dpp v77, v79 row_ror:1 row_mask:0xf bank_mask:0xf
	v_mov_b32_dpp v82, v68 row_shr:1 row_mask:0xf bank_mask:0xf
	v_mov_b32_dpp v83, v69 row_shr:1 row_mask:0xf bank_mask:0xf
	v_mov_b32_dpp v76, v70 row_shr:1 row_mask:0xf bank_mask:0xf
	v_mov_b32_dpp v77, v71 row_shr:1 row_mask:0xf bank_mask:0xf
	v_mov_b32_dpp v78, v72 row_ror:1 row_mask:0xf bank_mask:0xf
	v_mov_b32_dpp v79, v73 row_ror:1 row_mask:0xf bank_mask:0xf
	v_mov_b32_dpp v84, v74 row_ror:1 row_mask:0xf bank_mask:0xf
	v_mov_b32_dpp v85, v75 row_ror:1 row_mask:0xf bank_mask:0xf
	v_pk_fma_f32 v[72:73], v[140:141], v[76:77], v[148:149]
	v_pk_fma_f32 v[74:75], v[138:139], v[82:83], v[146:147]
	v_mov_b32_dpp v78, v64 row_shr:1 row_mask:0xf bank_mask:0xf
	v_mov_b32_dpp v79, v65 row_shr:1 row_mask:0xf bank_mask:0xf
	v_mov_b32_dpp v84, v66 row_shr:1 row_mask:0xf bank_mask:0xf
	v_mov_b32_dpp v85, v67 row_shr:1 row_mask:0xf bank_mask:0xf
	v_mov_b32_dpp v102, v70 row_shl:1 row_mask:0xf bank_mask:0xf
	v_mov_b32_dpp v103, v71 row_shl:1 row_mask:0xf bank_mask:0xf
	v_pk_fma_f32 v[76:77], v[68:69], v[142:143], v[74:75]
	v_pk_fma_f32 v[72:73], v[70:71], v[144:145], v[72:73]
	v_pk_fma_f32 v[78:79], v[126:127], v[78:79], v[134:135]
	v_pk_fma_f32 v[74:75], v[132:133], v[102:103], v[72:73]
	v_pk_fma_f32 v[72:73], v[130:131], v[100:101], v[76:77]
	v_pk_fma_f32 v[76:77], v[128:129], v[84:85], v[136:137]
	v_mov_b32_dpp v104, v64 row_shl:1 row_mask:0xf bank_mask:0xf
	v_mov_b32_dpp v105, v65 row_shl:1 row_mask:0xf bank_mask:0xf
	v_mov_b32_dpp v106, v66 row_shl:1 row_mask:0xf bank_mask:0xf
	v_mov_b32_dpp v107, v67 row_shl:1 row_mask:0xf bank_mask:0xf
	v_pk_fma_f32 v[82:83], v[64:65], v[122:123], v[78:79]
	v_pk_fma_f32 v[76:77], v[66:67], v[124:125], v[76:77]
	s_nop 0
	v_pk_fma_f32 v[78:79], v[120:121], v[106:107], v[76:77]
	v_pk_fma_f32 v[76:77], v[118:119], v[104:105], v[82:83]
	s_and_saveexec_b64 s[0:1], s[24:25]
	s_cbranch_execz .LBB0_951
	global_store_dwordx4 v[156:157], v[72:75], off
	global_store_dwordx4 v[156:157], v[76:79], off offset:512
	global_store_dwordx4 v[154:155], v[68:71], off
	global_store_dwordx4 v[154:155], v[64:67], off offset:512

; __device__ __forceinline__ unsigned cvt_pk_bf16(float lo, float hi) { unsigned r; asm volatile("v_cvt_pk_bf16_f32 %0, %1, %2" : "=v"(r) : "v"(lo), "v"(hi)); return r; }
; template <int CTRL> __device__ __forceinline__ f32x4 dpp4(f32x4 old, f32x4 src) { f32x4 r; r[0] = dppf<CTRL>(old[0], src[0]); r[1] = dppf<CTRL>(old[1], src[1]); r[2] = dppf<CTRL>(old[2], src[2]); r[3] = dppf<CTRL>(old[3], src[3]); return r; }
;     __device__ __forceinline__ void operator()(const f32x4 (&acc)[2][2][4][2], const Unit& u, int wr, int wc, int fr, int fq) const {
;     ...
;                 for (int m = 0; m < 4; ++m) {
;                     const f32x4 va = acc[ai][0][m][n], vb = acc[ai][1][m][n];
;                     f32x4 xa, xb, ya, yb;
;                     if (m == 0) { xa = haf; xb = hbf; } else { xa = dpp4<0x121>(va, acc[ai][0][m - 1][n]); xb = dpp4<0x121>(vb, acc[ai][1][m - 1][n]); }
;                     if (m == 3) { ya = hal; yb = hbl; } else { ya = dpp4<0x12F>(va, acc[ai][0][m + 1][n]); yb = dpp4<0x12F>(vb, acc[ai][1][m + 1][n]); }
;                     const f32x4 pa = dpp4<0x111>(xa, va), pb = dpp4<0x111>(xb, vb);
;                     const f32x4 na = dpp4<0x101>(ya, va), nb = dpp4<0x101>(yb, vb);
;                     const f32x4 ca = ba + w0a * pa + w1a * va + w2a * na, cbv = bb + w0b * pb + w1b * vb + w2b * nb;
;                     if (q == 0 && m == 0) { if (fr == 0) { const size_t o = (size_t)(u.pm * 2 + 0) * 11264 + u.pn * 256 + cl0 + 4 * n;
;                         *(f32x4*)(PART + o) = ca; *(f32x4*)(PART + o + 128) = cbv; *(f32x4*)(RAWB + o) = va; *(f32x4*)(RAWB + o + 128) = vb; } }
;                     if (q == 3 && m == 3) { if (fr == 15) { const size_t o = (size_t)(u.pm * 2 + 1) * 11264 + u.pn * 256 + cl0 + 4 * n;
;                         *(f32x4*)(PART + o) = ca; *(f32x4*)(PART + o + 128) = cbv; *(f32x4*)(RAWB + o) = va; *(f32x4*)(RAWB + o + 128) = vb; } }
;                     const f32x4 h = silu4(ca) * cbv;
;                     u32x2 pk; pk.x = cvt_pk_bf16(h[0], h[1]); pk.y = cvt_pk_bf16(h[2], h[3]);
;                     if (n == 0) pk0[ai][m] = pk;
;                     else { u32x4 w; w.x = pk0[ai][m].x; w.y = pk0[ai][m].y; w.z = pk.x; w.w = pk.y;
;                         __builtin_nontemporal_store(w, (u32x4*)(H + (size_t)(u.pm * BM + ai * HALF + wr * 64 + m * 16 + fr) * 5632 + u.pn * 128 + cl0)); }
.LBB0_955:
	s_waitcnt lgkmcnt(1)
	v_mov_b32_dpp v138, v62 row_shr:1 row_mask:0xf bank_mask:0xf
	v_mov_b32_dpp v139, v63 row_shr:1 row_mask:0xf bank_mask:0xf
	v_mov_b32_dpp v82, v54 row_ror:15 row_mask:0xf bank_mask:0xf
	v_mov_b32_dpp v83, v55 row_ror:15 row_mask:0xf bank_mask:0xf
	v_mov_b32_dpp v136, v60 row_shr:1 row_mask:0xf bank_mask:0xf
	v_mov_b32_dpp v137, v61 row_shr:1 row_mask:0xf bank_mask:0xf
	s_waitcnt vmcnt(1)
	v_pk_fma_f32 v[106:107], v[104:105], v[138:139], v[122:123]
	v_mov_b32_dpp v78, v52 row_ror:15 row_mask:0xf bank_mask:0xf
	v_mov_b32_dpp v79, v53 row_ror:15 row_mask:0xf bank_mask:0xf
	s_waitcnt lgkmcnt(0)
	v_mov_b32_dpp v132, v56 row_shr:1 row_mask:0xf bank_mask:0xf
	v_mov_b32_dpp v133, v57 row_shr:1 row_mask:0xf bank_mask:0xf
	v_mov_b32_dpp v82, v62 row_shl:1 row_mask:0xf bank_mask:0xf
	v_mov_b32_dpp v83, v63 row_shl:1 row_mask:0xf bank_mask:0xf
	v_pk_fma_f32 v[114:115], v[102:103], v[136:137], v[120:121]
	v_pk_fma_f32 v[106:107], v[62:63], v[118:119], v[106:107]
	v_mov_b32_dpp v90, v48 row_ror:15 row_mask:0xf bank_mask:0xf
	v_mov_b32_dpp v91, v49 row_ror:15 row_mask:0xf bank_mask:0xf
	v_mov_b32_dpp v134, v58 row_shr:1 row_mask:0xf bank_mask:0xf
	v_mov_b32_dpp v135, v59 row_shr:1 row_mask:0xf bank_mask:0xf
	v_mov_b32_dpp v78, v60 row_shl:1 row_mask:0xf bank_mask:0xf
	v_mov_b32_dpp v79, v61 row_shl:1 row_mask:0xf bank_mask:0xf
	v_pk_fma_f32 v[114:115], v[60:61], v[116:117], v[114:115]
	v_pk_fma_f32 v[138:139], v[86:87], v[82:83], v[106:107]
	s_waitcnt vmcnt(0)
	v_pk_fma_f32 v[82:83], v[74:75], v[132:133], v[92:93]
	v_or_b32_e32 v200, 4, v200
	v_mov_b32_dpp v100, v50 row_ror:15 row_mask:0xf bank_mask:0xf
	v_mov_b32_dpp v101, v51 row_ror:15 row_mask:0xf bank_mask:0xf
	v_mov_b32_dpp v90, v56 row_shl:1 row_mask:0xf bank_mask:0xf
	v_mov_b32_dpp v91, v57 row_shl:1 row_mask:0xf bank_mask:0xf
	v_pk_fma_f32 v[136:137], v[84:85], v[78:79], v[114:115]
	v_pk_fma_f32 v[78:79], v[76:77], v[134:135], v[94:95]
	v_pk_fma_f32 v[82:83], v[56:57], v[70:71], v[82:83]
	v_readlane_b32 s0, v242, 31
	v_mov_b32_dpp v100, v58 row_shl:1 row_mask:0xf bank_mask:0xf
	v_mov_b32_dpp v101, v59 row_shl:1 row_mask:0xf bank_mask:0xf
	v_pk_fma_f32 v[78:79], v[58:59], v[72:73], v[78:79]
	v_pk_fma_f32 v[132:133], v[66:67], v[90:91], v[82:83]
	v_lshlrev_b64 v[82:83], 2, v[200:201]
	v_readlane_b32 s1, v242, 32
	v_pk_fma_f32 v[134:135], v[68:69], v[100:101], v[78:79]
	v_lshl_add_u64 v[78:79], s[38:39], 0, v[82:83]
	v_lshl_add_u64 v[82:83], s[0:1], 0, v[82:83]
	s_and_saveexec_b64 s[0:1], s[8:9]
	s_cbranch_execz .LBB0_957
	global_store_dwordx4 v[82:83], v[136:139], off
	global_store_dwordx4 v[82:83], v[132:135], off offset:512
	global_store_dwordx4 v[78:79], v[60:63], off
	global_store_dwordx4 v[78:79], v[56:59], off offset:512
.LBB0_957:
	s_or_b64 exec, exec, s[0:1]
	v_mul_f32_e32 v90, 0xbfb8aa3b, v136
	v_mul_f32_e32 v91, 0xbfb8aa3b, v137
	v_exp_f32_e32 v90, v90
	v_exp_f32_e32 v91, v91
	v_mul_f32_e32 v100, 0xbfb8aa3b, v138
	v_mul_f32_e32 v101, 0xbfb8aa3b, v139
	v_exp_f32_e32 v100, v100
	v_exp_f32_e32 v101, v101
	v_add_f32_e32 v90, 1.0, v90
	v_add_f32_e32 v91, 1.0, v91
	v_rcp_f32_e32 v90, v90
	v_rcp_f32_e32 v91, v91
	v_add_f32_e32 v100, 1.0, v100
	v_add_f32_e32 v101, 1.0, v101
	v_rcp_f32_e32 v100, v100
	v_rcp_f32_e32 v101, v101
	v_pk_mul_f32 v[90:91], v[136:137], v[90:91]
	v_lshl_add_u32 v106, s94, 8, v213
	v_pk_mul_f32 v[90:91], v[132:133], v[90:91]
	v_pk_mul_f32 v[100:101], v[138:139], v[100:101]
	s_ashr_i32 s97, s96, 31
	v_pk_mul_f32 v[100:101], v[134:135], v[100:101]
	v_cvt_pk_bf16_f32 v114, v90, v91
	v_mov_b64_e32 v[90:91], s[36:37]
	v_cvt_pk_bf16_f32 v115, v100, v101
	v_mad_i64_i32 v[100:101], s[0:1], v106, s33, v[90:91]
	s_lshl_b64 s[18:19], s[96:97], 1
	v_lshl_add_u64 v[100:101], v[100:101], 0, s[18:19]
	v_lshl_add_u64 v[100:101], v[100:101], 0, v[186:187]
	global_store_dwordx4 v[100:101], v[112:115], off nt
	s_nop 0
	v_mov_b32_dpp v100, v60 row_ror:1 row_mask:0xf bank_mask:0xf
	v_mov_b32_dpp v101, v61 row_ror:1 row_mask:0xf bank_mask:0xf
	v_mov_b32_dpp v60, v62 row_ror:1 row_mask:0xf bank_mask:0xf
	v_mov_b32_dpp v61, v63 row_ror:1 row_mask:0xf bank_mask:0xf
	s_nop 0
	v_mov_b32_dpp v60, v54 row_shr:1 row_mask:0xf bank_mask:0xf
	s_nop 0
	v_mov_b32_dpp v61, v55 row_shr:1 row_mask:0xf bank_mask:0xf
	v_mov_b32_dpp v62, v56 row_ror:1 row_mask:0xf bank_mask:0xf
	v_mov_b32_dpp v63, v57 row_ror:1 row_mask:0xf bank_mask:0xf
	v_mov_b32_dpp v112, v46 row_ror:15 row_mask:0xf bank_mask:0xf
	v_mov_b32_dpp v113, v47 row_ror:15 row_mask:0xf bank_mask:0xf
	v_pk_fma_f32 v[60:61], v[104:105], v[60:61], v[122:123]
	v_mov_b32_dpp v56, v58 row_ror:1 row_mask:0xf bank_mask:0xf
	v_mov_b32_dpp v57, v59 row_ror:1 row_mask:0xf bank_mask:0xf
	v_mov_b32_dpp v100, v52 row_shr:1 row_mask:0xf bank_mask:0xf
	v_mov_b32_dpp v101, v53 row_shr:1 row_mask:0xf bank_mask:0xf
	v_mov_b32_dpp v112, v54 row_shl:1 row_mask:0xf bank_mask:0xf
	v_mov_b32_dpp v113, v55 row_shl:1 row_mask:0xf bank_mask:0xf
	v_pk_fma_f32 v[60:61], v[54:55], v[118:119], v[60:61]
	v_mov_b32_dpp v58, v44 row_ror:15 row_mask:0xf bank_mask:0xf
	v_mov_b32_dpp v59, v45 row_ror:15 row_mask:0xf bank_mask:0xf
	v_pk_fma_f32 v[100:101], v[102:103], v[100:101], v[120:121]
	v_pk_fma_f32 v[60:61], v[86:87], v[112:113], v[60:61]
	v_mov_b32_dpp v58, v52 row_shl:1 row_mask:0xf bank_mask:0xf
	v_mov_b32_dpp v59, v53 row_shl:1 row_mask:0xf bank_mask:0xf
	v_pk_fma_f32 v[100:101], v[52:53], v[116:117], v[100:101]
	v_mul_f32_e32 v107, 0xbfb8aa3b, v60
	v_pk_fma_f32 v[58:59], v[84:85], v[58:59], v[100:101]
	v_exp_f32_e32 v107, v107
	v_mul_f32_e32 v112, 0xbfb8aa3b, v61
	v_mul_f32_e32 v100, 0xbfb8aa3b, v58
	v_mul_f32_e32 v101, 0xbfb8aa3b, v59
; __device__ __forceinline__ unsigned cvt_pk_bf16(float lo, float hi) { unsigned r; asm volatile("v_cvt_pk_bf16_f32 %0, %1, %2" : "=v"(r) : "v"(lo), "v"(hi)); return r; }
; template <int CTRL> __device__ __forceinline__ f32x4 dpp4(f32x4 old, f32x4 src) { f32x4 r; r[0] = dppf<CTRL>(old[0], src[0]); r[1] = dppf<CTRL>(old[1], src[1]); r[2] = dppf<CTRL>(old[2], src[2]); r[3] = dppf<CTRL>(old[3], src[3]); return r; }
;     __device__ __forceinline__ void operator()(const f32x4 (&acc)[2][2][4][2], const Unit& u, int wr, int wc, int fr, int fq) const {
;     ...
;                 for (int m = 0; m < 4; ++m) {
;                     const f32x4 va = acc[ai][0][m][n], vb = acc[ai][1][m][n];
;                     f32x4 xa, xb, ya, yb;
;                     if (m == 0) { xa = haf; xb = hbf; } else { xa = dpp4<0x121>(va, acc[ai][0][m - 1][n]); xb = dpp4<0x121>(vb, acc[ai][1][m - 1][n]); }
;                     if (m == 3) { ya = hal; yb = hbl; } else { ya = dpp4<0x12F>(va, acc[ai][0][m + 1][n]); yb = dpp4<0x12F>(vb, acc[ai][1][m + 1][n]); }
;                     const f32x4 pa = dpp4<0x111>(xa, va), pb = dpp4<0x111>(xb, vb);
;                     const f32x4 na = dpp4<0x101>(ya, va), nb = dpp4<0x101>(yb, vb);
;                     const f32x4 ca = ba + w0a * pa + w1a * va + w2a * na, cbv = bb + w0b * pb + w1b * vb + w2b * nb;
;                     if (q == 0 && m == 0) { if (fr == 0) { const size_t o = (size_t)(u.pm * 2 + 0) * 11264 + u.pn * 256 + cl0 + 4 * n;
;                         *(f32x4*)(PART + o) = ca; *(f32x4*)(PART + o + 128) = cbv; *(f32x4*)(RAWB + o) = va; *(f32x4*)(RAWB + o + 128) = vb; } }
;                     if (q == 3 && m == 3) { if (fr == 15) { const size_t o = (size_t)(u.pm * 2 + 1) * 11264 + u.pn * 256 + cl0 + 4 * n;
;                         *(f32x4*)(PART + o) = ca; *(f32x4*)(PART + o + 128) = cbv; *(f32x4*)(RAWB + o) = va; *(f32x4*)(RAWB + o + 128) = vb; } }
;                     const f32x4 h = silu4(ca) * cbv;
;                     u32x2 pk; pk.x = cvt_pk_bf16(h[0], h[1]); pk.y = cvt_pk_bf16(h[2], h[3]);
;                     if (n == 0) pk0[ai][m] = pk;
;                     else { u32x4 w; w.x = pk0[ai][m].x; w.y = pk0[ai][m].y; w.z = pk.x; w.w = pk.y;
;                         __builtin_nontemporal_store(w, (u32x4*)(H + (size_t)(u.pm * BM + ai * HALF + wr * 64 + m * 16 + fr) * 5632 + u.pn * 128 + cl0)); }
	v_exp_f32_e32 v113, v112
	v_exp_f32_e32 v100, v100
	v_exp_f32_e32 v101, v101
	v_add_f32_e32 v107, 1.0, v107
	v_rcp_f32_e32 v112, v107
	v_add_f32_e32 v107, 1.0, v113
	v_add_f32_e32 v100, 1.0, v100
	v_add_f32_e32 v101, 1.0, v101
	v_rcp_f32_e32 v113, v107
	v_mov_b32_dpp v56, v50 row_shr:1 row_mask:0xf bank_mask:0xf
	v_mov_b32_dpp v57, v51 row_shr:1 row_mask:0xf bank_mask:0xf
	v_rcp_f32_e32 v100, v100
	v_rcp_f32_e32 v101, v101
	v_mov_b32_dpp v132, v42 row_ror:15 row_mask:0xf bank_mask:0xf
	v_mov_b32_dpp v133, v43 row_ror:15 row_mask:0xf bank_mask:0xf
	v_mov_b32_dpp v62, v48 row_shr:1 row_mask:0xf bank_mask:0xf
	v_mov_b32_dpp v63, v49 row_shr:1 row_mask:0xf bank_mask:0xf
	v_pk_fma_f32 v[56:57], v[76:77], v[56:57], v[94:95]
	v_mov_b32_dpp v114, v40 row_ror:15 row_mask:0xf bank_mask:0xf
	v_mov_b32_dpp v115, v41 row_ror:15 row_mask:0xf bank_mask:0xf
	v_mov_b32_dpp v132, v50 row_shl:1 row_mask:0xf bank_mask:0xf
	v_mov_b32_dpp v133, v51 row_shl:1 row_mask:0xf bank_mask:0xf
	v_pk_fma_f32 v[62:63], v[74:75], v[62:63], v[92:93]
	v_pk_fma_f32 v[56:57], v[50:51], v[72:73], v[56:57]
	v_mov_b32_dpp v114, v48 row_shl:1 row_mask:0xf bank_mask:0xf
	v_mov_b32_dpp v115, v49 row_shl:1 row_mask:0xf bank_mask:0xf
	v_pk_fma_f32 v[62:63], v[48:49], v[70:71], v[62:63]
	v_pk_fma_f32 v[56:57], v[68:69], v[132:133], v[56:57]
	v_pk_mul_f32 v[60:61], v[60:61], v[112:113]
	v_pk_fma_f32 v[62:63], v[66:67], v[114:115], v[62:63]
	v_pk_mul_f32 v[58:59], v[58:59], v[100:101]
	v_pk_mul_f32 v[56:57], v[56:57], v[60:61]
	v_pk_mul_f32 v[58:59], v[62:63], v[58:59]
	v_mov_b32_e32 v62, v42
	v_cvt_pk_bf16_f32 v112, v58, v59
	v_cvt_pk_bf16_f32 v113, v56, v57
	v_or_b32_e32 v56, 16, v106
	v_mad_i64_i32 v[56:57], s[0:1], v56, s33, v[90:91]
	v_lshl_add_u64 v[56:57], v[56:57], 0, s[18:19]
	v_lshl_add_u64 v[56:57], v[56:57], 0, v[186:187]
	global_store_dwordx4 v[56:57], v[110:113], off nt
	s_nop 0
	v_mov_b32_dpp v56, v52 row_ror:1 row_mask:0xf bank_mask:0xf
	v_mov_b32_dpp v57, v53 row_ror:1 row_mask:0xf bank_mask:0xf
	v_mov_b32_dpp v52, v54 row_ror:1 row_mask:0xf bank_mask:0xf
	v_mov_b32_dpp v53, v55 row_ror:1 row_mask:0xf bank_mask:0xf
	s_nop 0
	v_mov_b32_dpp v52, v46 row_shr:1 row_mask:0xf bank_mask:0xf
	v_mov_b32_dpp v54, v48 row_ror:1 row_mask:0xf bank_mask:0xf
	v_mov_b32_dpp v55, v49 row_ror:1 row_mask:0xf bank_mask:0xf
	v_mov_b32_dpp v53, v47 row_shr:1 row_mask:0xf bank_mask:0xf
	v_mov_b32_dpp v48, v50 row_ror:1 row_mask:0xf bank_mask:0xf
	v_mov_b32_dpp v49, v51 row_ror:1 row_mask:0xf bank_mask:0xf
	v_mov_b32_dpp v58, v38 row_ror:15 row_mask:0xf bank_mask:0xf
	v_mov_b32_dpp v59, v39 row_ror:15 row_mask:0xf bank_mask:0xf
	v_mov_b32_dpp v56, v44 row_shr:1 row_mask:0xf bank_mask:0xf
	v_mov_b32_dpp v57, v45 row_shr:1 row_mask:0xf bank_mask:0xf
	v_pk_fma_f32 v[52:53], v[104:105], v[52:53], v[122:123]
	v_mov_b32_dpp v50, v36 row_ror:15 row_mask:0xf bank_mask:0xf
	v_mov_b32_dpp v51, v37 row_ror:15 row_mask:0xf bank_mask:0xf
	v_mov_b32_dpp v58, v46 row_shl:1 row_mask:0xf bank_mask:0xf
	v_mov_b32_dpp v59, v47 row_shl:1 row_mask:0xf bank_mask:0xf
	v_pk_fma_f32 v[56:57], v[102:103], v[56:57], v[120:121]
	v_pk_fma_f32 v[52:53], v[46:47], v[118:119], v[52:53]
	v_mov_b32_dpp v50, v44 row_shl:1 row_mask:0xf bank_mask:0xf
	v_mov_b32_dpp v51, v45 row_shl:1 row_mask:0xf bank_mask:0xf
	v_pk_fma_f32 v[56:57], v[44:45], v[116:117], v[56:57]
	v_pk_fma_f32 v[52:53], v[86:87], v[58:59], v[52:53]
	v_pk_fma_f32 v[50:51], v[84:85], v[50:51], v[56:57]
	v_mul_f32_e32 v58, 0xbfb8aa3b, v52
	v_mul_f32_e32 v59, 0xbfb8aa3b, v53
	v_mul_f32_e32 v56, 0xbfb8aa3b, v50
	v_mul_f32_e32 v57, 0xbfb8aa3b, v51
	v_exp_f32_e32 v58, v58
	v_exp_f32_e32 v59, v59
	v_exp_f32_e32 v56, v56
	v_exp_f32_e32 v57, v57
	v_add_f32_e32 v58, 1.0, v58
	v_add_f32_e32 v59, 1.0, v59
	v_add_f32_e32 v56, 1.0, v56
	v_add_f32_e32 v57, 1.0, v57
	v_rcp_f32_e32 v58, v58
	v_rcp_f32_e32 v59, v59
	v_mov_b32_dpp v48, v42 row_shr:1 row_mask:0xf bank_mask:0xf
	v_mov_b32_dpp v49, v43 row_shr:1 row_mask:0xf bank_mask:0xf
	v_rcp_f32_e32 v56, v56
	v_rcp_f32_e32 v57, v57
; __device__ __forceinline__ unsigned cvt_pk_bf16(float lo, float hi) { unsigned r; asm volatile("v_cvt_pk_bf16_f32 %0, %1, %2" : "=v"(r) : "v"(lo), "v"(hi)); return r; }
; template <int CTRL> __device__ __forceinline__ f32x4 dpp4(f32x4 old, f32x4 src) { f32x4 r; r[0] = dppf<CTRL>(old[0], src[0]); r[1] = dppf<CTRL>(old[1], src[1]); r[2] = dppf<CTRL>(old[2], src[2]); r[3] = dppf<CTRL>(old[3], src[3]); return r; }
;     __device__ __forceinline__ void operator()(const f32x4 (&acc)[2][2][4][2], const Unit& u, int wr, int wc, int fr, int fq) const {
;     ...
;                 for (int m = 0; m < 4; ++m) {
;                     const f32x4 va = acc[ai][0][m][n], vb = acc[ai][1][m][n];
;                     f32x4 xa, xb, ya, yb;
;                     if (m == 0) { xa = haf; xb = hbf; } else { xa = dpp4<0x121>(va, acc[ai][0][m - 1][n]); xb = dpp4<0x121>(vb, acc[ai][1][m - 1][n]); }
;                     if (m == 3) { ya = hal; yb = hbl; } else { ya = dpp4<0x12F>(va, acc[ai][0][m + 1][n]); yb = dpp4<0x12F>(vb, acc[ai][1][m + 1][n]); }
;                     const f32x4 pa = dpp4<0x111>(xa, va), pb = dpp4<0x111>(xb, vb);
;                     const f32x4 na = dpp4<0x101>(ya, va), nb = dpp4<0x101>(yb, vb);
;                     const f32x4 ca = ba + w0a * pa + w1a * va + w2a * na, cbv = bb + w0b * pb + w1b * vb + w2b * nb;
;                     if (q == 0 && m == 0) { if (fr == 0) { const size_t o = (size_t)(u.pm * 2 + 0) * 11264 + u.pn * 256 + cl0 + 4 * n;
;                         *(f32x4*)(PART + o) = ca; *(f32x4*)(PART + o + 128) = cbv; *(f32x4*)(RAWB + o) = va; *(f32x4*)(RAWB + o + 128) = vb; } }
;                     if (q == 3 && m == 3) { if (fr == 15) { const size_t o = (size_t)(u.pm * 2 + 1) * 11264 + u.pn * 256 + cl0 + 4 * n;
;                         *(f32x4*)(PART + o) = ca; *(f32x4*)(PART + o + 128) = cbv; *(f32x4*)(RAWB + o) = va; *(f32x4*)(RAWB + o + 128) = vb; } }
;                     const f32x4 h = silu4(ca) * cbv;
;                     u32x2 pk; pk.x = cvt_pk_bf16(h[0], h[1]); pk.y = cvt_pk_bf16(h[2], h[3]);
;                     if (n == 0) pk0[ai][m] = pk;
;                     else { u32x4 w; w.x = pk0[ai][m].x; w.y = pk0[ai][m].y; w.z = pk.x; w.w = pk.y;
;                         __builtin_nontemporal_store(w, (u32x4*)(H + (size_t)(u.pm * BM + ai * HALF + wr * 64 + m * 16 + fr) * 5632 + u.pn * 128 + cl0)); }
	v_mov_b32_dpp v62, v34 row_ror:15 row_mask:0xf bank_mask:0xf
	v_mov_b32_dpp v63, v35 row_ror:15 row_mask:0xf bank_mask:0xf
	v_mov_b32_dpp v54, v40 row_shr:1 row_mask:0xf bank_mask:0xf
	v_mov_b32_dpp v55, v41 row_shr:1 row_mask:0xf bank_mask:0xf
	v_pk_fma_f32 v[48:49], v[76:77], v[48:49], v[94:95]
	v_mov_b32_dpp v60, v32 row_ror:15 row_mask:0xf bank_mask:0xf
	v_mov_b32_dpp v61, v33 row_ror:15 row_mask:0xf bank_mask:0xf
	v_mov_b32_dpp v62, v42 row_shl:1 row_mask:0xf bank_mask:0xf
	v_mov_b32_dpp v63, v43 row_shl:1 row_mask:0xf bank_mask:0xf
	v_pk_fma_f32 v[54:55], v[74:75], v[54:55], v[92:93]
	v_pk_fma_f32 v[48:49], v[42:43], v[72:73], v[48:49]
	v_mov_b32_dpp v60, v40 row_shl:1 row_mask:0xf bank_mask:0xf
	v_mov_b32_dpp v61, v41 row_shl:1 row_mask:0xf bank_mask:0xf
	v_pk_fma_f32 v[54:55], v[40:41], v[70:71], v[54:55]
	v_pk_fma_f32 v[48:49], v[68:69], v[62:63], v[48:49]
	v_pk_mul_f32 v[52:53], v[52:53], v[58:59]
	v_pk_fma_f32 v[54:55], v[66:67], v[60:61], v[54:55]
	v_pk_mul_f32 v[50:51], v[50:51], v[56:57]
	v_pk_mul_f32 v[48:49], v[48:49], v[52:53]
	v_pk_mul_f32 v[50:51], v[54:55], v[50:51]
	v_mov_b32_dpp v124, v36 row_shl:1 row_mask:0xf bank_mask:0xf
	v_cvt_pk_bf16_f32 v110, v50, v51
	v_cvt_pk_bf16_f32 v111, v48, v49
	v_or_b32_e32 v48, 32, v106
	v_mad_i64_i32 v[48:49], s[0:1], v48, s33, v[90:91]
	v_lshl_add_u64 v[48:49], v[48:49], 0, s[18:19]
	v_lshl_add_u64 v[48:49], v[48:49], 0, v[186:187]
	global_store_dwordx4 v[48:49], v[108:111], off nt
	s_nop 0
	v_mov_b32_dpp v48, v44 row_ror:1 row_mask:0xf bank_mask:0xf
	v_mov_b32_dpp v49, v45 row_ror:1 row_mask:0xf bank_mask:0xf
	v_mov_b32_dpp v44, v46 row_ror:1 row_mask:0xf bank_mask:0xf
	v_mov_b32_dpp v45, v47 row_ror:1 row_mask:0xf bank_mask:0xf
	v_mov_b32_dpp v48, v36 row_shr:1 row_mask:0xf bank_mask:0xf
	v_mov_b32_dpp v49, v37 row_shr:1 row_mask:0xf bank_mask:0xf
	v_mov_b32_dpp v44, v38 row_shr:1 row_mask:0xf bank_mask:0xf
	v_mov_b32_dpp v45, v39 row_shr:1 row_mask:0xf bank_mask:0xf
	v_mov_b32_dpp v46, v40 row_ror:1 row_mask:0xf bank_mask:0xf
	v_mov_b32_dpp v47, v41 row_ror:1 row_mask:0xf bank_mask:0xf
	v_mov_b32_dpp v50, v42 row_ror:1 row_mask:0xf bank_mask:0xf
	v_mov_b32_dpp v51, v43 row_ror:1 row_mask:0xf bank_mask:0xf
	v_pk_fma_f32 v[40:41], v[104:105], v[44:45], v[122:123]
	v_pk_fma_f32 v[42:43], v[102:103], v[48:49], v[120:121]
	v_mov_b32_dpp v46, v32 row_shr:1 row_mask:0xf bank_mask:0xf
	v_mov_b32_dpp v47, v33 row_shr:1 row_mask:0xf bank_mask:0xf
	v_mov_b32_dpp v50, v34 row_shr:1 row_mask:0xf bank_mask:0xf
	v_mov_b32_dpp v51, v35 row_shr:1 row_mask:0xf bank_mask:0xf
	v_mov_b32_dpp v125, v37 row_shl:1 row_mask:0xf bank_mask:0xf
	v_mov_b32_dpp v126, v38 row_shl:1 row_mask:0xf bank_mask:0xf
	v_mov_b32_dpp v127, v39 row_shl:1 row_mask:0xf bank_mask:0xf
	v_pk_fma_f32 v[44:45], v[36:37], v[116:117], v[42:43]
	v_pk_fma_f32 v[40:41], v[38:39], v[118:119], v[40:41]
	v_or_b32_e32 v198, 4, v198
	v_pk_fma_f32 v[42:43], v[86:87], v[126:127], v[40:41]
	v_pk_fma_f32 v[40:41], v[84:85], v[124:125], v[44:45]
	v_pk_fma_f32 v[44:45], v[76:77], v[50:51], v[94:95]
	v_pk_fma_f32 v[46:47], v[74:75], v[46:47], v[92:93]
	v_readlane_b32 s0, v242, 31
	v_mov_b32_dpp v128, v32 row_shl:1 row_mask:0xf bank_mask:0xf
	v_mov_b32_dpp v129, v33 row_shl:1 row_mask:0xf bank_mask:0xf
	v_mov_b32_dpp v130, v34 row_shl:1 row_mask:0xf bank_mask:0xf
	v_mov_b32_dpp v131, v35 row_shl:1 row_mask:0xf bank_mask:0xf
	v_pk_fma_f32 v[48:49], v[32:33], v[70:71], v[46:47]
	v_pk_fma_f32 v[44:45], v[34:35], v[72:73], v[44:45]
	v_lshlrev_b64 v[50:51], 2, v[198:199]
	v_readlane_b32 s1, v242, 32
	v_pk_fma_f32 v[46:47], v[68:69], v[130:131], v[44:45]
	v_pk_fma_f32 v[44:45], v[66:67], v[128:129], v[48:49]
	v_lshl_add_u64 v[48:49], s[38:39], 0, v[50:51]
	v_lshl_add_u64 v[50:51], s[0:1], 0, v[50:51]
	s_and_saveexec_b64 s[0:1], s[50:51]
	s_cbranch_execz .LBB0_959
	global_store_dwordx4 v[50:51], v[40:43], off
	global_store_dwordx4 v[50:51], v[44:47], off offset:512
	global_store_dwordx4 v[48:49], v[36:39], off
	global_store_dwordx4 v[48:49], v[32:35], off offset:512

; __device__ __forceinline__ unsigned cvt_pk_bf16(float lo, float hi) { unsigned r; asm volatile("v_cvt_pk_bf16_f32 %0, %1, %2" : "=v"(r) : "v"(lo), "v"(hi)); return r; }
; template <int CTRL> __device__ __forceinline__ f32x4 dpp4(f32x4 old, f32x4 src) { f32x4 r; r[0] = dppf<CTRL>(old[0], src[0]); r[1] = dppf<CTRL>(old[1], src[1]); r[2] = dppf<CTRL>(old[2], src[2]); r[3] = dppf<CTRL>(old[3], src[3]); return r; }
;     __device__ __forceinline__ void operator()(const f32x4 (&acc)[2][2][4][2], const Unit& u, int wr, int wc, int fr, int fq) const {
;     ...
;                 for (int m = 0; m < 4; ++m) {
;                     const f32x4 va = acc[ai][0][m][n], vb = acc[ai][1][m][n];
;                     f32x4 xa, xb, ya, yb;
;                     if (m == 0) { xa = haf; xb = hbf; } else { xa = dpp4<0x121>(va, acc[ai][0][m - 1][n]); xb = dpp4<0x121>(vb, acc[ai][1][m - 1][n]); }
;                     if (m == 3) { ya = hal; yb = hbl; } else { ya = dpp4<0x12F>(va, acc[ai][0][m + 1][n]); yb = dpp4<0x12F>(vb, acc[ai][1][m + 1][n]); }
;                     const f32x4 pa = dpp4<0x111>(xa, va), pb = dpp4<0x111>(xb, vb);
;                     const f32x4 na = dpp4<0x101>(ya, va), nb = dpp4<0x101>(yb, vb);
;                     const f32x4 ca = ba + w0a * pa + w1a * va + w2a * na, cbv = bb + w0b * pb + w1b * vb + w2b * nb;
;                     if (q == 0 && m == 0) { if (fr == 0) { const size_t o = (size_t)(u.pm * 2 + 0) * 11264 + u.pn * 256 + cl0 + 4 * n;
;                         *(f32x4*)(PART + o) = ca; *(f32x4*)(PART + o + 128) = cbv; *(f32x4*)(RAWB + o) = va; *(f32x4*)(RAWB + o + 128) = vb; } }
;                     if (q == 3 && m == 3) { if (fr == 15) { const size_t o = (size_t)(u.pm * 2 + 1) * 11264 + u.pn * 256 + cl0 + 4 * n;
;                         *(f32x4*)(PART + o) = ca; *(f32x4*)(PART + o + 128) = cbv; *(f32x4*)(RAWB + o) = va; *(f32x4*)(RAWB + o + 128) = vb; } }
;                     const f32x4 h = silu4(ca) * cbv;
;                     u32x2 pk; pk.x = cvt_pk_bf16(h[0], h[1]); pk.y = cvt_pk_bf16(h[2], h[3]);
;                     if (n == 0) pk0[ai][m] = pk;
;                     else { u32x4 w; w.x = pk0[ai][m].x; w.y = pk0[ai][m].y; w.z = pk.x; w.w = pk.y;
;                         __builtin_nontemporal_store(w, (u32x4*)(H + (size_t)(u.pm * BM + ai * HALF + wr * 64 + m * 16 + fr) * 5632 + u.pn * 128 + cl0)); }
.LBB0_963:
	s_waitcnt lgkmcnt(1)
	v_mov_b32_dpp v44, v28 row_shr:1 row_mask:0xf bank_mask:0xf
	v_mov_b32_dpp v45, v29 row_shr:1 row_mask:0xf bank_mask:0xf
	v_mov_b32_dpp v46, v30 row_shr:1 row_mask:0xf bank_mask:0xf
	v_mov_b32_dpp v47, v31 row_shr:1 row_mask:0xf bank_mask:0xf
	s_waitcnt lgkmcnt(0)
	v_mov_b32_dpp v40, v24 row_shr:1 row_mask:0xf bank_mask:0xf
	v_mov_b32_dpp v41, v25 row_shr:1 row_mask:0xf bank_mask:0xf
	v_mov_b32_dpp v42, v26 row_shr:1 row_mask:0xf bank_mask:0xf
	v_mov_b32_dpp v43, v27 row_shr:1 row_mask:0xf bank_mask:0xf
	v_mov_b32_dpp v52, v20 row_ror:15 row_mask:0xf bank_mask:0xf
	v_mov_b32_dpp v53, v21 row_ror:15 row_mask:0xf bank_mask:0xf
	v_mov_b32_dpp v54, v22 row_ror:15 row_mask:0xf bank_mask:0xf
	v_mov_b32_dpp v55, v23 row_ror:15 row_mask:0xf bank_mask:0xf
	v_mov_b32_dpp v56, v16 row_ror:15 row_mask:0xf bank_mask:0xf
	v_mov_b32_dpp v57, v17 row_ror:15 row_mask:0xf bank_mask:0xf
	v_mov_b32_dpp v58, v18 row_ror:15 row_mask:0xf bank_mask:0xf
	v_mov_b32_dpp v59, v19 row_ror:15 row_mask:0xf bank_mask:0xf
	v_pk_fma_f32 v[46:47], v[104:105], v[46:47], v[122:123]
	v_pk_fma_f32 v[44:45], v[102:103], v[44:45], v[120:121]
	v_pk_fma_f32 v[42:43], v[76:77], v[42:43], v[94:95]
	v_pk_fma_f32 v[40:41], v[74:75], v[40:41], v[92:93]
	v_mov_b32_dpp v52, v28 row_shl:1 row_mask:0xf bank_mask:0xf
	v_mov_b32_dpp v53, v29 row_shl:1 row_mask:0xf bank_mask:0xf
	v_mov_b32_dpp v54, v30 row_shl:1 row_mask:0xf bank_mask:0xf
	v_mov_b32_dpp v55, v31 row_shl:1 row_mask:0xf bank_mask:0xf
	v_mov_b32_dpp v56, v24 row_shl:1 row_mask:0xf bank_mask:0xf
	v_mov_b32_dpp v57, v25 row_shl:1 row_mask:0xf bank_mask:0xf
	v_mov_b32_dpp v58, v26 row_shl:1 row_mask:0xf bank_mask:0xf
	v_mov_b32_dpp v59, v27 row_shl:1 row_mask:0xf bank_mask:0xf
	v_pk_fma_f32 v[44:45], v[28:29], v[116:117], v[44:45]
	v_pk_fma_f32 v[46:47], v[30:31], v[118:119], v[46:47]
	v_pk_fma_f32 v[40:41], v[24:25], v[70:71], v[40:41]
	v_pk_fma_f32 v[42:43], v[26:27], v[72:73], v[42:43]
	v_pk_fma_f32 v[46:47], v[86:87], v[54:55], v[46:47]
	v_pk_fma_f32 v[44:45], v[84:85], v[52:53], v[44:45]
	v_pk_fma_f32 v[42:43], v[68:69], v[58:59], v[42:43]
	v_pk_fma_f32 v[40:41], v[66:67], v[56:57], v[40:41]
	s_and_saveexec_b64 s[0:1], s[10:11]
	s_cbranch_execz .LBB0_965
	global_store_dwordx4 v[82:83], v[44:47], off
	global_store_dwordx4 v[82:83], v[40:43], off offset:512
	global_store_dwordx4 v[78:79], v[28:31], off
	global_store_dwordx4 v[78:79], v[24:27], off offset:512
.LBB0_965:
	s_or_b64 exec, exec, s[0:1]
	v_mul_f32_e32 v52, 0xbfb8aa3b, v44
	v_mul_f32_e32 v53, 0xbfb8aa3b, v45
	v_exp_f32_e32 v52, v52
	v_exp_f32_e32 v53, v53
	v_mul_f32_e32 v54, 0xbfb8aa3b, v46
	v_mul_f32_e32 v55, 0xbfb8aa3b, v47
	v_exp_f32_e32 v54, v54
	v_exp_f32_e32 v55, v55
	v_add_f32_e32 v52, 1.0, v52
	v_add_f32_e32 v53, 1.0, v53
	v_rcp_f32_e32 v52, v52
	v_rcp_f32_e32 v53, v53
	v_add_f32_e32 v54, 1.0, v54
	v_add_f32_e32 v55, 1.0, v55
	v_rcp_f32_e32 v54, v54
	v_rcp_f32_e32 v55, v55
	v_pk_mul_f32 v[44:45], v[44:45], v[52:53]
	v_add_u32_e32 v56, 0x80, v106
	v_pk_mul_f32 v[40:41], v[40:41], v[44:45]
	v_pk_mul_f32 v[46:47], v[46:47], v[54:55]
	v_cvt_pk_bf16_f32 v98, v40, v41
	v_mov_b64_e32 v[40:41], s[36:37]
	v_pk_mul_f32 v[42:43], v[42:43], v[46:47]
	v_cvt_pk_bf16_f32 v99, v42, v43
	v_mad_i64_i32 v[42:43], s[0:1], v56, s33, v[40:41]
	v_lshl_add_u64 v[42:43], v[42:43], 0, s[18:19]
	v_lshl_add_u64 v[42:43], v[42:43], 0, v[186:187]
	global_store_dwordx4 v[42:43], v[96:99], off nt
	s_nop 0
	v_mov_b32_dpp v42, v28 row_ror:1 row_mask:0xf bank_mask:0xf
	v_mov_b32_dpp v43, v29 row_ror:1 row_mask:0xf bank_mask:0xf
	v_mov_b32_dpp v44, v14 row_ror:15 row_mask:0xf bank_mask:0xf
	v_mov_b32_dpp v28, v30 row_ror:1 row_mask:0xf bank_mask:0xf
	v_mov_b32_dpp v29, v31 row_ror:1 row_mask:0xf bank_mask:0xf
	s_nop 0
	v_mov_b32_dpp v28, v22 row_shr:1 row_mask:0xf bank_mask:0xf
	v_mov_b32_dpp v30, v24 row_ror:1 row_mask:0xf bank_mask:0xf
	v_mov_b32_dpp v31, v25 row_ror:1 row_mask:0xf bank_mask:0xf
	v_mov_b32_dpp v29, v23 row_shr:1 row_mask:0xf bank_mask:0xf
	v_mov_b32_dpp v24, v26 row_ror:1 row_mask:0xf bank_mask:0xf
	v_mov_b32_dpp v25, v27 row_ror:1 row_mask:0xf bank_mask:0xf
	v_mov_b32_dpp v45, v15 row_ror:15 row_mask:0xf bank_mask:0xf
	v_mov_b32_dpp v42, v20 row_shr:1 row_mask:0xf bank_mask:0xf
	v_mov_b32_dpp v43, v21 row_shr:1 row_mask:0xf bank_mask:0xf
	v_pk_fma_f32 v[28:29], v[104:105], v[28:29], v[122:123]
	v_mov_b32_dpp v26, v12 row_ror:15 row_mask:0xf bank_mask:0xf
	v_mov_b32_dpp v27, v13 row_ror:15 row_mask:0xf bank_mask:0xf
	v_mov_b32_dpp v44, v22 row_shl:1 row_mask:0xf bank_mask:0xf
	v_mov_b32_dpp v45, v23 row_shl:1 row_mask:0xf bank_mask:0xf
	v_pk_fma_f32 v[42:43], v[102:103], v[42:43], v[120:121]
	v_pk_fma_f32 v[28:29], v[22:23], v[118:119], v[28:29]
	v_mov_b32_dpp v26, v20 row_shl:1 row_mask:0xf bank_mask:0xf
	v_mov_b32_dpp v27, v21 row_shl:1 row_mask:0xf bank_mask:0xf
	v_pk_fma_f32 v[42:43], v[20:21], v[116:117], v[42:43]
	v_pk_fma_f32 v[28:29], v[86:87], v[44:45], v[28:29]
	v_pk_fma_f32 v[26:27], v[84:85], v[26:27], v[42:43]
	v_mul_f32_e32 v44, 0xbfb8aa3b, v28
	v_mul_f32_e32 v45, 0xbfb8aa3b, v29
	v_mul_f32_e32 v42, 0xbfb8aa3b, v26
	v_mul_f32_e32 v43, 0xbfb8aa3b, v27
	v_exp_f32_e32 v44, v44
	v_exp_f32_e32 v45, v45
	v_exp_f32_e32 v42, v42
	v_exp_f32_e32 v43, v43
	v_add_f32_e32 v44, 1.0, v44
	v_add_f32_e32 v45, 1.0, v45
	v_add_f32_e32 v42, 1.0, v42
	v_add_f32_e32 v43, 1.0, v43
	v_rcp_f32_e32 v44, v44
	v_rcp_f32_e32 v45, v45
	v_mov_b32_dpp v24, v18 row_shr:1 row_mask:0xf bank_mask:0xf
	v_mov_b32_dpp v25, v19 row_shr:1 row_mask:0xf bank_mask:0xf
	v_rcp_f32_e32 v42, v42
	v_rcp_f32_e32 v43, v43
	v_mov_b32_dpp v52, v10 row_ror:15 row_mask:0xf bank_mask:0xf
; __device__ __forceinline__ unsigned cvt_pk_bf16(float lo, float hi) { unsigned r; asm volatile("v_cvt_pk_bf16_f32 %0, %1, %2" : "=v"(r) : "v"(lo), "v"(hi)); return r; }
; template <int CTRL> __device__ __forceinline__ f32x4 dpp4(f32x4 old, f32x4 src) { f32x4 r; r[0] = dppf<CTRL>(old[0], src[0]); r[1] = dppf<CTRL>(old[1], src[1]); r[2] = dppf<CTRL>(old[2], src[2]); r[3] = dppf<CTRL>(old[3], src[3]); return r; }
;     __device__ __forceinline__ void operator()(const f32x4 (&acc)[2][2][4][2], const Unit& u, int wr, int wc, int fr, int fq) const {
;     ...
;                 for (int m = 0; m < 4; ++m) {
;                     const f32x4 va = acc[ai][0][m][n], vb = acc[ai][1][m][n];
;                     f32x4 xa, xb, ya, yb;
;                     if (m == 0) { xa = haf; xb = hbf; } else { xa = dpp4<0x121>(va, acc[ai][0][m - 1][n]); xb = dpp4<0x121>(vb, acc[ai][1][m - 1][n]); }
;                     if (m == 3) { ya = hal; yb = hbl; } else { ya = dpp4<0x12F>(va, acc[ai][0][m + 1][n]); yb = dpp4<0x12F>(vb, acc[ai][1][m + 1][n]); }
;                     const f32x4 pa = dpp4<0x111>(xa, va), pb = dpp4<0x111>(xb, vb);
;                     const f32x4 na = dpp4<0x101>(ya, va), nb = dpp4<0x101>(yb, vb);
;                     const f32x4 ca = ba + w0a * pa + w1a * va + w2a * na, cbv = bb + w0b * pb + w1b * vb + w2b * nb;
;                     if (q == 0 && m == 0) { if (fr == 0) { const size_t o = (size_t)(u.pm * 2 + 0) * 11264 + u.pn * 256 + cl0 + 4 * n;
;                         *(f32x4*)(PART + o) = ca; *(f32x4*)(PART + o + 128) = cbv; *(f32x4*)(RAWB + o) = va; *(f32x4*)(RAWB + o + 128) = vb; } }
;                     if (q == 3 && m == 3) { if (fr == 15) { const size_t o = (size_t)(u.pm * 2 + 1) * 11264 + u.pn * 256 + cl0 + 4 * n;
;                         *(f32x4*)(PART + o) = ca; *(f32x4*)(PART + o + 128) = cbv; *(f32x4*)(RAWB + o) = va; *(f32x4*)(RAWB + o + 128) = vb; } }
;                     const f32x4 h = silu4(ca) * cbv;
;                     u32x2 pk; pk.x = cvt_pk_bf16(h[0], h[1]); pk.y = cvt_pk_bf16(h[2], h[3]);
;                     if (n == 0) pk0[ai][m] = pk;
;                     else { u32x4 w; w.x = pk0[ai][m].x; w.y = pk0[ai][m].y; w.z = pk.x; w.w = pk.y;
;                         __builtin_nontemporal_store(w, (u32x4*)(H + (size_t)(u.pm * BM + ai * HALF + wr * 64 + m * 16 + fr) * 5632 + u.pn * 128 + cl0)); }
	v_mov_b32_dpp v53, v11 row_ror:15 row_mask:0xf bank_mask:0xf
	v_mov_b32_dpp v30, v16 row_shr:1 row_mask:0xf bank_mask:0xf
	v_mov_b32_dpp v31, v17 row_shr:1 row_mask:0xf bank_mask:0xf
	v_pk_fma_f32 v[24:25], v[76:77], v[24:25], v[94:95]
	v_mov_b32_dpp v46, v8 row_ror:15 row_mask:0xf bank_mask:0xf
	v_mov_b32_dpp v47, v9 row_ror:15 row_mask:0xf bank_mask:0xf
	v_mov_b32_dpp v52, v18 row_shl:1 row_mask:0xf bank_mask:0xf
	v_mov_b32_dpp v53, v19 row_shl:1 row_mask:0xf bank_mask:0xf
	v_pk_fma_f32 v[30:31], v[74:75], v[30:31], v[92:93]
	v_pk_fma_f32 v[24:25], v[18:19], v[72:73], v[24:25]
	v_mov_b32_dpp v46, v16 row_shl:1 row_mask:0xf bank_mask:0xf
	v_mov_b32_dpp v47, v17 row_shl:1 row_mask:0xf bank_mask:0xf
	v_pk_fma_f32 v[30:31], v[16:17], v[70:71], v[30:31]
	v_pk_fma_f32 v[24:25], v[68:69], v[52:53], v[24:25]
	v_pk_mul_f32 v[28:29], v[28:29], v[44:45]
	v_pk_fma_f32 v[30:31], v[66:67], v[46:47], v[30:31]
	v_pk_mul_f32 v[26:27], v[26:27], v[42:43]
	v_pk_mul_f32 v[24:25], v[24:25], v[28:29]
	v_pk_mul_f32 v[26:27], v[30:31], v[26:27]
	v_mov_b32_e32 v30, v10
	v_cvt_pk_bf16_f32 v90, v26, v27
	v_cvt_pk_bf16_f32 v91, v24, v25
	v_add_u32_e32 v24, 0x90, v106
	v_mad_i64_i32 v[24:25], s[0:1], v24, s33, v[40:41]
	v_lshl_add_u64 v[24:25], v[24:25], 0, s[18:19]
	v_lshl_add_u64 v[24:25], v[24:25], 0, v[186:187]
	global_store_dwordx4 v[24:25], v[88:91], off nt
	s_nop 0
	v_mov_b32_dpp v24, v20 row_ror:1 row_mask:0xf bank_mask:0xf
	v_mov_b32_dpp v25, v21 row_ror:1 row_mask:0xf bank_mask:0xf
	v_mov_b32_dpp v20, v22 row_ror:1 row_mask:0xf bank_mask:0xf
	v_mov_b32_dpp v21, v23 row_ror:1 row_mask:0xf bank_mask:0xf
	s_nop 0
	v_mov_b32_dpp v20, v14 row_shr:1 row_mask:0xf bank_mask:0xf
	v_mov_b32_dpp v22, v16 row_ror:1 row_mask:0xf bank_mask:0xf
	v_mov_b32_dpp v23, v17 row_ror:1 row_mask:0xf bank_mask:0xf
	v_mov_b32_dpp v21, v15 row_shr:1 row_mask:0xf bank_mask:0xf
	v_mov_b32_dpp v16, v18 row_ror:1 row_mask:0xf bank_mask:0xf
	v_mov_b32_dpp v17, v19 row_ror:1 row_mask:0xf bank_mask:0xf
	v_mov_b32_dpp v26, v6 row_ror:15 row_mask:0xf bank_mask:0xf
	v_mov_b32_dpp v27, v7 row_ror:15 row_mask:0xf bank_mask:0xf
	v_mov_b32_dpp v24, v12 row_shr:1 row_mask:0xf bank_mask:0xf
	v_mov_b32_dpp v25, v13 row_shr:1 row_mask:0xf bank_mask:0xf
	v_pk_fma_f32 v[20:21], v[104:105], v[20:21], v[122:123]
	v_mov_b32_dpp v18, v4 row_ror:15 row_mask:0xf bank_mask:0xf
	v_mov_b32_dpp v19, v5 row_ror:15 row_mask:0xf bank_mask:0xf
	v_mov_b32_dpp v26, v14 row_shl:1 row_mask:0xf bank_mask:0xf
	v_mov_b32_dpp v27, v15 row_shl:1 row_mask:0xf bank_mask:0xf
	v_pk_fma_f32 v[24:25], v[102:103], v[24:25], v[120:121]
	v_pk_fma_f32 v[20:21], v[14:15], v[118:119], v[20:21]
	v_mov_b32_dpp v18, v12 row_shl:1 row_mask:0xf bank_mask:0xf
	v_mov_b32_dpp v19, v13 row_shl:1 row_mask:0xf bank_mask:0xf
	v_pk_fma_f32 v[24:25], v[12:13], v[116:117], v[24:25]
	v_pk_fma_f32 v[20:21], v[86:87], v[26:27], v[20:21]
	v_pk_fma_f32 v[18:19], v[84:85], v[18:19], v[24:25]
	v_mul_f32_e32 v26, 0xbfb8aa3b, v20
	v_mul_f32_e32 v27, 0xbfb8aa3b, v21
	v_mul_f32_e32 v24, 0xbfb8aa3b, v18
	v_mul_f32_e32 v25, 0xbfb8aa3b, v19
	v_exp_f32_e32 v26, v26
	v_exp_f32_e32 v27, v27
	v_exp_f32_e32 v24, v24
	v_exp_f32_e32 v25, v25
	v_add_f32_e32 v26, 1.0, v26
	v_add_f32_e32 v27, 1.0, v27
	v_add_f32_e32 v24, 1.0, v24
	v_add_f32_e32 v25, 1.0, v25
	v_rcp_f32_e32 v26, v26
	v_rcp_f32_e32 v27, v27
	v_mov_b32_dpp v16, v10 row_shr:1 row_mask:0xf bank_mask:0xf
	v_mov_b32_dpp v17, v11 row_shr:1 row_mask:0xf bank_mask:0xf
	v_rcp_f32_e32 v24, v24
	v_rcp_f32_e32 v25, v25
	v_mov_b32_dpp v30, v2 row_ror:15 row_mask:0xf bank_mask:0xf
	v_mov_b32_dpp v31, v3 row_ror:15 row_mask:0xf bank_mask:0xf
	v_mov_b32_dpp v22, v8 row_shr:1 row_mask:0xf bank_mask:0xf
	v_mov_b32_dpp v23, v9 row_shr:1 row_mask:0xf bank_mask:0xf
	v_pk_fma_f32 v[16:17], v[76:77], v[16:17], v[94:95]
	v_mov_b32_dpp v28, v0 row_ror:15 row_mask:0xf bank_mask:0xf
	v_mov_b32_dpp v29, v1 row_ror:15 row_mask:0xf bank_mask:0xf
	v_mov_b32_dpp v30, v10 row_shl:1 row_mask:0xf bank_mask:0xf
	v_mov_b32_dpp v31, v11 row_shl:1 row_mask:0xf bank_mask:0xf
	v_pk_fma_f32 v[22:23], v[74:75], v[22:23], v[92:93]
	v_pk_fma_f32 v[16:17], v[10:11], v[72:73], v[16:17]
	v_mov_b32_dpp v28, v8 row_shl:1 row_mask:0xf bank_mask:0xf
	v_mov_b32_dpp v29, v9 row_shl:1 row_mask:0xf bank_mask:0xf
	v_pk_fma_f32 v[22:23], v[8:9], v[70:71], v[22:23]
	v_pk_fma_f32 v[16:17], v[68:69], v[30:31], v[16:17]
	v_pk_mul_f32 v[20:21], v[20:21], v[26:27]
	v_pk_fma_f32 v[22:23], v[66:67], v[28:29], v[22:23]
	v_pk_mul_f32 v[18:19], v[18:19], v[24:25]
	v_pk_mul_f32 v[16:17], v[16:17], v[20:21]
	v_pk_mul_f32 v[18:19], v[22:23], v[18:19]
	v_mov_b32_dpp v32, v4 row_shl:1 row_mask:0xf bank_mask:0xf
	v_cvt_pk_bf16_f32 v82, v18, v19
	v_cvt_pk_bf16_f32 v83, v16, v17
	v_add_u32_e32 v16, 0xa0, v106
	v_mad_i64_i32 v[16:17], s[0:1], v16, s33, v[40:41]
	v_lshl_add_u64 v[16:17], v[16:17], 0, s[18:19]
	v_lshl_add_u64 v[16:17], v[16:17], 0, v[186:187]
	global_store_dwordx4 v[16:17], v[80:83], off nt
	s_nop 0
	v_mov_b32_dpp v16, v12 row_ror:1 row_mask:0xf bank_mask:0xf
	v_mov_b32_dpp v17, v13 row_ror:1 row_mask:0xf bank_mask:0xf
	v_mov_b32_dpp v12, v14 row_ror:1 row_mask:0xf bank_mask:0xf
	v_mov_b32_dpp v13, v15 row_ror:1 row_mask:0xf bank_mask:0xf
	v_mov_b32_dpp v16, v4 row_shr:1 row_mask:0xf bank_mask:0xf
	v_mov_b32_dpp v17, v5 row_shr:1 row_mask:0xf bank_mask:0xf
	v_mov_b32_dpp v12, v6 row_shr:1 row_mask:0xf bank_mask:0xf
	v_mov_b32_dpp v13, v7 row_shr:1 row_mask:0xf bank_mask:0xf
	v_mov_b32_dpp v14, v8 row_ror:1 row_mask:0xf bank_mask:0xf
	v_mov_b32_dpp v15, v9 row_ror:1 row_mask:0xf bank_mask:0xf
	v_mov_b32_dpp v18, v10 row_ror:1 row_mask:0xf bank_mask:0xf
	v_mov_b32_dpp v19, v11 row_ror:1 row_mask:0xf bank_mask:0xf
	v_pk_fma_f32 v[8:9], v[104:105], v[12:13], v[122:123]
	v_pk_fma_f32 v[10:11], v[102:103], v[16:17], v[120:121]
	v_mov_b32_dpp v14, v0 row_shr:1 row_mask:0xf bank_mask:0xf
	v_mov_b32_dpp v15, v1 row_shr:1 row_mask:0xf bank_mask:0xf
	v_mov_b32_dpp v18, v2 row_shr:1 row_mask:0xf bank_mask:0xf
	v_mov_b32_dpp v19, v3 row_shr:1 row_mask:0xf bank_mask:0xf
	v_mov_b32_dpp v33, v5 row_shl:1 row_mask:0xf bank_mask:0xf
	v_mov_b32_dpp v34, v6 row_shl:1 row_mask:0xf bank_mask:0xf
	v_mov_b32_dpp v35, v7 row_shl:1 row_mask:0xf bank_mask:0xf
	v_pk_fma_f32 v[12:13], v[4:5], v[116:117], v[10:11]
	v_pk_fma_f32 v[8:9], v[6:7], v[118:119], v[8:9]
	v_pk_fma_f32 v[14:15], v[74:75], v[14:15], v[92:93]
	v_pk_fma_f32 v[10:11], v[86:87], v[34:35], v[8:9]
	v_pk_fma_f32 v[8:9], v[84:85], v[32:33], v[12:13]
	v_pk_fma_f32 v[12:13], v[76:77], v[18:19], v[94:95]
	v_mov_b32_dpp v36, v0 row_shl:1 row_mask:0xf bank_mask:0xf
	v_mov_b32_dpp v37, v1 row_shl:1 row_mask:0xf bank_mask:0xf
	v_mov_b32_dpp v38, v2 row_shl:1 row_mask:0xf bank_mask:0xf
	v_mov_b32_dpp v39, v3 row_shl:1 row_mask:0xf bank_mask:0xf
	v_pk_fma_f32 v[16:17], v[0:1], v[70:71], v[14:15]
	v_pk_fma_f32 v[12:13], v[2:3], v[72:73], v[12:13]
	s_nop 0
	v_pk_fma_f32 v[14:15], v[68:69], v[38:39], v[12:13]
	v_pk_fma_f32 v[12:13], v[66:67], v[36:37], v[16:17]
	s_and_saveexec_b64 s[0:1], s[24:25]
	s_cbranch_execz .LBB0_967
;     __device__ __forceinline__ void operator()(const f32x4 (&acc)[2][2][4][2], const Unit& u, int wr, int wc, int fr, int fq) const {
;     ...
;                     if (q == 0 && m == 0) { if (fr == 0) { const size_t o = (size_t)(u.pm * 2 + 0) * 11264 + u.pn * 256 + cl0 + 4 * n;
;                         *(f32x4*)(PART + o) = ca; *(f32x4*)(PART + o + 128) = cbv; *(f32x4*)(RAWB + o) = va; *(f32x4*)(RAWB + o + 128) = vb; } }
;                     if (q == 3 && m == 3) { if (fr == 15) { const size_t o = (size_t)(u.pm * 2 + 1) * 11264 + u.pn * 256 + cl0 + 4 * n;
;                         *(f32x4*)(PART + o) = ca; *(f32x4*)(PART + o + 128) = cbv; *(f32x4*)(RAWB + o) = va; *(f32x4*)(RAWB + o + 128) = vb; } }
	global_store_dwordx4 v[50:51], v[8:11], off
	global_store_dwordx4 v[50:51], v[12:15], off offset:512
	global_store_dwordx4 v[48:49], v[4:7], off
	global_store_dwordx4 v[48:49], v[0:3], off offset:512
